# A/B: per-phase s_setprio flips deleted in the seven GEMM phases (112 instructions); on top of v112
# speedup vs baseline: 1.0042x; 1.0020x over previous
.LBB0_301:
	s_add_i32 s58, s0, 2
	s_add_u32 s59, s8, 0xfffc0080
	s_addc_u32 s1, s9, -1
	s_add_i32 s65, 0, 0x10000
	s_cmp_eq_u32 s46, s0
	s_cselect_b32 s1, s21, s1
	s_cselect_b32 s0, s55, s59
	v_add_u32_e32 v142, s65, v145
	s_cselect_b32 s67, s23, s27
	s_cselect_b32 s66, s22, s26
	s_add_i32 s59, 0, 0x14000
	ds_read_b128 v[148:151], v142
	ds_read_b128 v[152:155], v142 offset:1024
	ds_read_b128 v[156:159], v142 offset:2048
	ds_read_b128 v[160:163], v142 offset:3072
	v_add_u32_e32 v142, s59, v145
	ds_read_b128 v[164:167], v142
	ds_read_b128 v[168:171], v142 offset:1024
	ds_read_b128 v[172:175], v142 offset:2048
	ds_read_b128 v[188:191], v142 offset:3072
	v_lshl_add_u64 v[142:143], s[8:9], 0, v[138:139]
	s_add_i32 m0, s34, 0xc000
	ds_read_b128 v[192:195], v147
	ds_read_b128 v[196:199], v147 offset:1024
	ds_read_b128 v[200:203], v147 offset:2048
	ds_read_b128 v[204:207], v147 offset:3072
	ds_read_b128 v[208:211], v147 offset:4096
	ds_read_b128 v[212:215], v147 offset:5120
	ds_read_b128 v[216:219], v147 offset:6144
	ds_read_b128 v[220:223], v147 offset:7168
	global_load_lds_dwordx4 v[142:143], off
	v_lshl_add_u64 v[142:143], s[8:9], 0, v[140:141]
	s_add_i32 m0, s34, 0xe000
	s_nop 0
	global_load_lds_dwordx4 v[142:143], off
	s_waitcnt vmcnt(8)
	s_waitcnt lgkmcnt(0)
	s_barrier
	s_waitcnt lgkmcnt(0)
	v_mfma_f32_16x16x32_bf16 v[124:127], v[148:151], v[192:195], v[124:127]
	v_mfma_f32_16x16x32_bf16 v[120:123], v[156:159], v[192:195], v[120:123]
	v_mfma_f32_16x16x32_bf16 v[108:111], v[148:151], v[200:203], v[108:111]
	v_mfma_f32_16x16x32_bf16 v[104:107], v[156:159], v[200:203], v[104:107]
	v_mfma_f32_16x16x32_bf16 v[92:95], v[148:151], v[208:211], v[92:95]
	v_mfma_f32_16x16x32_bf16 v[88:91], v[156:159], v[208:211], v[88:91]
	v_mfma_f32_16x16x32_bf16 v[76:79], v[148:151], v[216:219], v[76:79]
	v_mfma_f32_16x16x32_bf16 v[72:75], v[156:159], v[216:219], v[72:75]
	v_mfma_f32_16x16x32_bf16 v[124:127], v[152:155], v[196:199], v[124:127]
	v_mfma_f32_16x16x32_bf16 v[120:123], v[160:163], v[196:199], v[120:123]
	v_mfma_f32_16x16x32_bf16 v[108:111], v[152:155], v[204:207], v[108:111]
	v_mfma_f32_16x16x32_bf16 v[104:107], v[160:163], v[204:207], v[104:107]
	v_mfma_f32_16x16x32_bf16 v[92:95], v[152:155], v[212:215], v[92:95]
	v_mfma_f32_16x16x32_bf16 v[88:91], v[160:163], v[212:215], v[88:91]
	v_mfma_f32_16x16x32_bf16 v[76:79], v[152:155], v[220:223], v[76:79]
	v_mfma_f32_16x16x32_bf16 v[72:75], v[160:163], v[220:223], v[72:75]
	v_mfma_f32_16x16x32_bf16 v[116:119], v[164:167], v[192:195], v[116:119]
	v_mfma_f32_16x16x32_bf16 v[112:115], v[172:175], v[192:195], v[112:115]
	v_mfma_f32_16x16x32_bf16 v[100:103], v[164:167], v[200:203], v[100:103]
	v_mfma_f32_16x16x32_bf16 v[96:99], v[172:175], v[200:203], v[96:99]
	v_mfma_f32_16x16x32_bf16 v[84:87], v[164:167], v[208:211], v[84:87]
	v_mfma_f32_16x16x32_bf16 v[80:83], v[172:175], v[208:211], v[80:83]
	v_mfma_f32_16x16x32_bf16 v[68:71], v[164:167], v[216:219], v[68:71]
	v_mfma_f32_16x16x32_bf16 v[64:67], v[172:175], v[216:219], v[64:67]
	v_mfma_f32_16x16x32_bf16 v[116:119], v[168:171], v[196:199], v[116:119]
	v_mfma_f32_16x16x32_bf16 v[112:115], v[188:191], v[196:199], v[112:115]
	v_mfma_f32_16x16x32_bf16 v[100:103], v[168:171], v[204:207], v[100:103]
	v_mfma_f32_16x16x32_bf16 v[96:99], v[188:191], v[204:207], v[96:99]
	v_mfma_f32_16x16x32_bf16 v[84:87], v[168:171], v[212:215], v[84:87]
	v_mfma_f32_16x16x32_bf16 v[80:83], v[188:191], v[212:215], v[80:83]
	v_mfma_f32_16x16x32_bf16 v[68:71], v[168:171], v[220:223], v[68:71]
	v_mfma_f32_16x16x32_bf16 v[64:67], v[188:191], v[220:223], v[64:67]
	s_barrier
	s_add_i32 s65, s65, s33
	v_lshl_add_u64 v[142:143], s[66:67], 0, v[132:133]
	s_mov_b32 m0, s65
	ds_read_b128 v[192:195], v147 offset:16384
	ds_read_b128 v[196:199], v147 offset:17408
	ds_read_b128 v[200:203], v147 offset:18432
	ds_read_b128 v[204:207], v147 offset:19456
	ds_read_b128 v[208:211], v147 offset:20480
	ds_read_b128 v[212:215], v147 offset:21504
	ds_read_b128 v[216:219], v147 offset:22528
	ds_read_b128 v[220:223], v147 offset:23552
	global_load_lds_dwordx4 v[142:143], off
	s_add_i32 m0, s65, 0x2000
	v_lshl_add_u64 v[238:239], s[66:67], 0, v[128:129]
	s_add_u32 s66, s66, s10
	s_addc_u32 s67, s67, s11
	s_add_i32 s59, s59, s33
	global_load_lds_dwordx4 v[238:239], off
	v_lshl_add_u64 v[240:241], s[66:67], 0, v[132:133]
	s_mov_b32 m0, s59
	v_lshl_add_u64 v[242:243], s[66:67], 0, v[128:129]
	global_load_lds_dwordx4 v[240:241], off
	s_add_i32 m0, s59, 0x2000
	v_lshl_add_u64 v[244:245], s[0:1], 0, v[134:135]
	global_load_lds_dwordx4 v[242:243], off
	s_mov_b32 m0, s34
	v_lshl_add_u64 v[246:247], s[0:1], 0, v[130:131]
	global_load_lds_dwordx4 v[244:245], off
	s_mov_b32 m0, s35
	s_nop 0
	global_load_lds_dwordx4 v[246:247], off
	s_waitcnt vmcnt(8)
	s_waitcnt lgkmcnt(0)
	s_barrier
	s_waitcnt lgkmcnt(0)
	v_mfma_f32_16x16x32_bf16 v[60:63], v[148:151], v[192:195], v[60:63]
	v_mfma_f32_16x16x32_bf16 v[56:59], v[156:159], v[192:195], v[56:59]
	v_mfma_f32_16x16x32_bf16 v[44:47], v[148:151], v[200:203], v[44:47]
	v_mfma_f32_16x16x32_bf16 v[40:43], v[156:159], v[200:203], v[40:43]
	v_mfma_f32_16x16x32_bf16 v[28:31], v[148:151], v[208:211], v[28:31]
	v_mfma_f32_16x16x32_bf16 v[24:27], v[156:159], v[208:211], v[24:27]
	v_mfma_f32_16x16x32_bf16 v[12:15], v[148:151], v[216:219], v[12:15]
	v_mfma_f32_16x16x32_bf16 v[8:11], v[156:159], v[216:219], v[8:11]
	v_mfma_f32_16x16x32_bf16 v[60:63], v[152:155], v[196:199], v[60:63]
	v_mfma_f32_16x16x32_bf16 v[56:59], v[160:163], v[196:199], v[56:59]
	v_mfma_f32_16x16x32_bf16 v[44:47], v[152:155], v[204:207], v[44:47]
	v_mfma_f32_16x16x32_bf16 v[40:43], v[160:163], v[204:207], v[40:43]
	v_mfma_f32_16x16x32_bf16 v[28:31], v[152:155], v[212:215], v[28:31]
	v_mfma_f32_16x16x32_bf16 v[24:27], v[160:163], v[212:215], v[24:27]
	v_mfma_f32_16x16x32_bf16 v[12:15], v[152:155], v[220:223], v[12:15]
	v_mfma_f32_16x16x32_bf16 v[8:11], v[160:163], v[220:223], v[8:11]
	v_mfma_f32_16x16x32_bf16 v[52:55], v[164:167], v[192:195], v[52:55]
	v_mfma_f32_16x16x32_bf16 v[48:51], v[172:175], v[192:195], v[48:51]
	v_mfma_f32_16x16x32_bf16 v[36:39], v[164:167], v[200:203], v[36:39]
	v_mfma_f32_16x16x32_bf16 v[32:35], v[172:175], v[200:203], v[32:35]
	v_mfma_f32_16x16x32_bf16 v[20:23], v[164:167], v[208:211], v[20:23]
	v_mfma_f32_16x16x32_bf16 v[16:19], v[172:175], v[208:211], v[16:19]
	v_mfma_f32_16x16x32_bf16 v[4:7], v[164:167], v[216:219], v[4:7]
	v_mfma_f32_16x16x32_bf16 v[0:3], v[172:175], v[216:219], v[0:3]
	v_mfma_f32_16x16x32_bf16 v[52:55], v[168:171], v[196:199], v[52:55]
	v_mfma_f32_16x16x32_bf16 v[48:51], v[188:191], v[196:199], v[48:51]
	v_mfma_f32_16x16x32_bf16 v[36:39], v[168:171], v[204:207], v[36:39]
	v_mfma_f32_16x16x32_bf16 v[32:35], v[188:191], v[204:207], v[32:35]
	v_mfma_f32_16x16x32_bf16 v[20:23], v[168:171], v[212:215], v[20:23]
	v_mfma_f32_16x16x32_bf16 v[16:19], v[188:191], v[212:215], v[16:19]
	v_mfma_f32_16x16x32_bf16 v[4:7], v[168:171], v[220:223], v[4:7]
	v_mfma_f32_16x16x32_bf16 v[0:3], v[188:191], v[220:223], v[0:3]
	s_barrier
	s_add_i32 s59, 0, 0x18000
	s_add_i32 s65, 0, 0x1c000
	v_add_u32_e32 v160, s59, v145
	v_add_u32_e32 v178, s65, v145
	ds_read_b128 v[148:151], v160
	ds_read_b128 v[152:155], v160 offset:1024
	ds_read_b128 v[156:159], v160 offset:2048
	ds_read_b128 v[160:163], v160 offset:3072
	ds_read_b128 v[164:167], v178
	ds_read_b128 v[168:171], v178 offset:1024
	ds_read_b128 v[172:175], v178 offset:2048
	ds_read_b128 v[188:191], v178 offset:3072
	s_add_u32 s0, s0, 0x40000
	s_addc_u32 s1, s1, 0
	s_mov_b32 m0, s36
	v_lshl_add_u64 v[248:249], s[0:1], 0, v[134:135]
	ds_read_b128 v[192:195], v147 offset:32768
	ds_read_b128 v[196:199], v147 offset:33792
	ds_read_b128 v[200:203], v147 offset:34816
	ds_read_b128 v[204:207], v147 offset:35840
	ds_read_b128 v[208:211], v147 offset:36864
	ds_read_b128 v[212:215], v147 offset:37888
	ds_read_b128 v[216:219], v147 offset:38912
	ds_read_b128 v[220:223], v147 offset:39936
	global_load_lds_dwordx4 v[248:249], off
	v_lshl_add_u64 v[248:249], s[0:1], 0, v[130:131]
	s_mov_b32 m0, s37
	s_nop 0
	global_load_lds_dwordx4 v[248:249], off
	s_waitcnt vmcnt(8)
	s_waitcnt lgkmcnt(0)
	s_barrier
	s_waitcnt lgkmcnt(0)
	v_mfma_f32_16x16x32_bf16 v[124:127], v[148:151], v[192:195], v[124:127]
	v_mfma_f32_16x16x32_bf16 v[120:123], v[156:159], v[192:195], v[120:123]
	v_mfma_f32_16x16x32_bf16 v[108:111], v[148:151], v[200:203], v[108:111]
	v_mfma_f32_16x16x32_bf16 v[104:107], v[156:159], v[200:203], v[104:107]
	v_mfma_f32_16x16x32_bf16 v[92:95], v[148:151], v[208:211], v[92:95]
	v_mfma_f32_16x16x32_bf16 v[88:91], v[156:159], v[208:211], v[88:91]
	v_mfma_f32_16x16x32_bf16 v[76:79], v[148:151], v[216:219], v[76:79]
	v_mfma_f32_16x16x32_bf16 v[72:75], v[156:159], v[216:219], v[72:75]
	v_mfma_f32_16x16x32_bf16 v[124:127], v[152:155], v[196:199], v[124:127]
	v_mfma_f32_16x16x32_bf16 v[120:123], v[160:163], v[196:199], v[120:123]
	v_mfma_f32_16x16x32_bf16 v[108:111], v[152:155], v[204:207], v[108:111]
	v_mfma_f32_16x16x32_bf16 v[104:107], v[160:163], v[204:207], v[104:107]
	v_mfma_f32_16x16x32_bf16 v[92:95], v[152:155], v[212:215], v[92:95]
	v_mfma_f32_16x16x32_bf16 v[88:91], v[160:163], v[212:215], v[88:91]
	v_mfma_f32_16x16x32_bf16 v[76:79], v[152:155], v[220:223], v[76:79]
	v_mfma_f32_16x16x32_bf16 v[72:75], v[160:163], v[220:223], v[72:75]
	v_mfma_f32_16x16x32_bf16 v[116:119], v[164:167], v[192:195], v[116:119]
	v_mfma_f32_16x16x32_bf16 v[112:115], v[172:175], v[192:195], v[112:115]
	v_mfma_f32_16x16x32_bf16 v[100:103], v[164:167], v[200:203], v[100:103]
	v_mfma_f32_16x16x32_bf16 v[96:99], v[172:175], v[200:203], v[96:99]
	v_mfma_f32_16x16x32_bf16 v[84:87], v[164:167], v[208:211], v[84:87]
	v_mfma_f32_16x16x32_bf16 v[80:83], v[172:175], v[208:211], v[80:83]
	v_mfma_f32_16x16x32_bf16 v[68:71], v[164:167], v[216:219], v[68:71]
	v_mfma_f32_16x16x32_bf16 v[64:67], v[172:175], v[216:219], v[64:67]
	v_mfma_f32_16x16x32_bf16 v[116:119], v[168:171], v[196:199], v[116:119]
	v_mfma_f32_16x16x32_bf16 v[112:115], v[188:191], v[196:199], v[112:115]
	v_mfma_f32_16x16x32_bf16 v[100:103], v[168:171], v[204:207], v[100:103]
	v_mfma_f32_16x16x32_bf16 v[96:99], v[188:191], v[204:207], v[96:99]
	v_mfma_f32_16x16x32_bf16 v[84:87], v[168:171], v[212:215], v[84:87]
	v_mfma_f32_16x16x32_bf16 v[80:83], v[188:191], v[212:215], v[80:83]
	v_mfma_f32_16x16x32_bf16 v[68:71], v[168:171], v[220:223], v[68:71]
	v_mfma_f32_16x16x32_bf16 v[64:67], v[188:191], v[220:223], v[64:67]
	s_barrier
	s_add_i32 s0, s59, s33
	v_lshl_add_u64 v[142:143], v[142:143], 0, s[96:97]
	s_mov_b32 m0, s0
	ds_read_b128 v[192:195], v147 offset:49152
	ds_read_b128 v[196:199], v147 offset:50176
	ds_read_b128 v[200:203], v147 offset:51200
	ds_read_b128 v[204:207], v147 offset:52224
	ds_read_b128 v[208:211], v147 offset:53248
	ds_read_b128 v[212:215], v147 offset:54272
	ds_read_b128 v[216:219], v147 offset:55296
	ds_read_b128 v[220:223], v147 offset:56320
	global_load_lds_dwordx4 v[142:143], off
	v_lshl_add_u64 v[142:143], v[238:239], 0, s[96:97]
	s_add_i32 m0, s0, 0x2000
	s_add_i32 s0, s65, s33
	global_load_lds_dwordx4 v[142:143], off
	v_lshl_add_u64 v[142:143], v[240:241], 0, s[96:97]
	s_mov_b32 m0, s0
	s_nop 0
	global_load_lds_dwordx4 v[142:143], off
	v_lshl_add_u64 v[142:143], v[242:243], 0, s[96:97]
	s_add_i32 m0, s0, 0x2000
	s_nop 0
	global_load_lds_dwordx4 v[142:143], off
	v_lshl_add_u64 v[142:143], v[244:245], 0, s[96:97]
	s_mov_b32 m0, s42
	s_nop 0
	global_load_lds_dwordx4 v[142:143], off
	v_lshl_add_u64 v[142:143], v[246:247], 0, s[96:97]
	s_mov_b32 m0, s44
	s_nop 0
	global_load_lds_dwordx4 v[142:143], off
	s_waitcnt vmcnt(8)
	s_waitcnt lgkmcnt(0)
	s_barrier
	s_waitcnt lgkmcnt(0)
	v_mfma_f32_16x16x32_bf16 v[60:63], v[148:151], v[192:195], v[60:63]
	v_mfma_f32_16x16x32_bf16 v[56:59], v[156:159], v[192:195], v[56:59]
	v_mfma_f32_16x16x32_bf16 v[44:47], v[148:151], v[200:203], v[44:47]
	v_mfma_f32_16x16x32_bf16 v[40:43], v[156:159], v[200:203], v[40:43]
	v_mfma_f32_16x16x32_bf16 v[28:31], v[148:151], v[208:211], v[28:31]
	v_mfma_f32_16x16x32_bf16 v[24:27], v[156:159], v[208:211], v[24:27]
	v_mfma_f32_16x16x32_bf16 v[12:15], v[148:151], v[216:219], v[12:15]
	v_mfma_f32_16x16x32_bf16 v[8:11], v[156:159], v[216:219], v[8:11]
	v_mfma_f32_16x16x32_bf16 v[60:63], v[152:155], v[196:199], v[60:63]
	v_mfma_f32_16x16x32_bf16 v[56:59], v[160:163], v[196:199], v[56:59]
	v_mfma_f32_16x16x32_bf16 v[44:47], v[152:155], v[204:207], v[44:47]
	v_mfma_f32_16x16x32_bf16 v[40:43], v[160:163], v[204:207], v[40:43]
	v_mfma_f32_16x16x32_bf16 v[28:31], v[152:155], v[212:215], v[28:31]
	v_mfma_f32_16x16x32_bf16 v[24:27], v[160:163], v[212:215], v[24:27]
	v_mfma_f32_16x16x32_bf16 v[12:15], v[152:155], v[220:223], v[12:15]
	v_mfma_f32_16x16x32_bf16 v[8:11], v[160:163], v[220:223], v[8:11]
	v_mfma_f32_16x16x32_bf16 v[52:55], v[164:167], v[192:195], v[52:55]
	v_mfma_f32_16x16x32_bf16 v[48:51], v[172:175], v[192:195], v[48:51]
	v_mfma_f32_16x16x32_bf16 v[36:39], v[164:167], v[200:203], v[36:39]
	v_mfma_f32_16x16x32_bf16 v[32:35], v[172:175], v[200:203], v[32:35]
	v_mfma_f32_16x16x32_bf16 v[20:23], v[164:167], v[208:211], v[20:23]
	v_mfma_f32_16x16x32_bf16 v[16:19], v[172:175], v[208:211], v[16:19]
	v_mfma_f32_16x16x32_bf16 v[4:7], v[164:167], v[216:219], v[4:7]
	v_mfma_f32_16x16x32_bf16 v[0:3], v[172:175], v[216:219], v[0:3]
	v_mfma_f32_16x16x32_bf16 v[52:55], v[168:171], v[196:199], v[52:55]
	v_mfma_f32_16x16x32_bf16 v[48:51], v[188:191], v[196:199], v[48:51]
	v_mfma_f32_16x16x32_bf16 v[36:39], v[168:171], v[204:207], v[36:39]
	v_mfma_f32_16x16x32_bf16 v[32:35], v[188:191], v[204:207], v[32:35]
	v_mfma_f32_16x16x32_bf16 v[20:23], v[168:171], v[212:215], v[20:23]
	v_mfma_f32_16x16x32_bf16 v[16:19], v[188:191], v[212:215], v[16:19]
	v_mfma_f32_16x16x32_bf16 v[4:7], v[168:171], v[220:223], v[4:7]
	v_mfma_f32_16x16x32_bf16 v[0:3], v[188:191], v[220:223], v[0:3]
	s_barrier
	s_add_u32 s8, s8, 0x100
	s_addc_u32 s9, s9, 0
	s_add_u32 s26, s26, 0x100
	s_addc_u32 s27, s27, 0
	s_cmp_ge_i32 s58, s45
	s_mov_b32 s0, s58
	s_cbranch_scc0 .LBB0_301
	v_readlane_b32 s66, v254, 46
	v_readlane_b32 s67, v254, 47
	v_readlane_b32 s65, v254, 48

.LBB0_378:
	s_add_i32 s45, s44, 2
	s_add_u32 s0, s4, 0xffff0080
	s_addc_u32 s1, s5, -1
	s_add_i32 s59, 0, 0x10000
	s_cmp_eq_u32 s51, s44
	s_cselect_b32 s1, s23, s1
	s_cselect_b32 s0, s29, s0
	s_cselect_b32 s67, s25, s7
	s_cselect_b32 s66, s24, s6
	s_add_i32 s44, 0, 0x14000
	s_waitcnt vmcnt(0)
	v_add_u32_e32 v92, s59, v163
	v_add_u32_e32 v160, s44, v163
	ds_read_b128 v[72:75], v92
	ds_read_b128 v[76:79], v92 offset:1024
	ds_read_b128 v[80:83], v92 offset:2048
	ds_read_b128 v[92:95], v92 offset:3072
	ds_read_b128 v[156:159], v160
	ds_read_b128 v[166:169], v160 offset:1024
	ds_read_b128 v[170:173], v160 offset:2048
	ds_read_b128 v[188:191], v160 offset:3072
	v_lshl_add_u64 v[160:161], s[4:5], 0, v[152:153]
	s_add_i32 m0, s36, 0xc000
	ds_read_b128 v[192:195], v165
	ds_read_b128 v[196:199], v165 offset:1024
	ds_read_b128 v[200:203], v165 offset:2048
	ds_read_b128 v[204:207], v165 offset:3072
	ds_read_b128 v[208:211], v165 offset:4096
	ds_read_b128 v[212:215], v165 offset:5120
	ds_read_b128 v[216:219], v165 offset:6144
	ds_read_b128 v[220:223], v165 offset:7168
	global_load_lds_dwordx4 v[160:161], off
	v_lshl_add_u64 v[160:161], s[4:5], 0, v[154:155]
	s_add_i32 m0, s36, 0xe000
	s_nop 0
	global_load_lds_dwordx4 v[160:161], off
	s_waitcnt vmcnt(8)
	s_waitcnt lgkmcnt(0)
	s_barrier
	s_waitcnt lgkmcnt(0)
	v_mfma_f32_16x16x32_bf16 v[140:143], v[72:75], v[192:195], v[140:143]
	v_mfma_f32_16x16x32_bf16 v[136:139], v[80:83], v[192:195], v[136:139]
	v_mfma_f32_16x16x32_bf16 v[124:127], v[72:75], v[200:203], v[124:127]
	v_mfma_f32_16x16x32_bf16 v[120:123], v[80:83], v[200:203], v[120:123]
	v_mfma_f32_16x16x32_bf16 v[108:111], v[72:75], v[208:211], v[108:111]
	v_mfma_f32_16x16x32_bf16 v[104:107], v[80:83], v[208:211], v[104:107]
	v_mfma_f32_16x16x32_bf16 v[88:91], v[72:75], v[216:219], v[88:91]
	v_mfma_f32_16x16x32_bf16 v[84:87], v[80:83], v[216:219], v[84:87]
	v_mfma_f32_16x16x32_bf16 v[140:143], v[76:79], v[196:199], v[140:143]
	v_mfma_f32_16x16x32_bf16 v[136:139], v[92:95], v[196:199], v[136:139]
	v_mfma_f32_16x16x32_bf16 v[124:127], v[76:79], v[204:207], v[124:127]
	v_mfma_f32_16x16x32_bf16 v[120:123], v[92:95], v[204:207], v[120:123]
	v_mfma_f32_16x16x32_bf16 v[108:111], v[76:79], v[212:215], v[108:111]
	v_mfma_f32_16x16x32_bf16 v[104:107], v[92:95], v[212:215], v[104:107]
	v_mfma_f32_16x16x32_bf16 v[88:91], v[76:79], v[220:223], v[88:91]
	v_mfma_f32_16x16x32_bf16 v[84:87], v[92:95], v[220:223], v[84:87]
	v_mfma_f32_16x16x32_bf16 v[132:135], v[156:159], v[192:195], v[132:135]
	v_mfma_f32_16x16x32_bf16 v[128:131], v[170:173], v[192:195], v[128:131]
	v_mfma_f32_16x16x32_bf16 v[116:119], v[156:159], v[200:203], v[116:119]
	v_mfma_f32_16x16x32_bf16 v[112:115], v[170:173], v[200:203], v[112:115]
	v_mfma_f32_16x16x32_bf16 v[100:103], v[156:159], v[208:211], v[100:103]
	v_mfma_f32_16x16x32_bf16 v[96:99], v[170:173], v[208:211], v[96:99]
	v_mfma_f32_16x16x32_bf16 v[68:71], v[156:159], v[216:219], v[68:71]
	v_mfma_f32_16x16x32_bf16 v[64:67], v[170:173], v[216:219], v[64:67]
	v_mfma_f32_16x16x32_bf16 v[132:135], v[166:169], v[196:199], v[132:135]
	v_mfma_f32_16x16x32_bf16 v[128:131], v[188:191], v[196:199], v[128:131]
	v_mfma_f32_16x16x32_bf16 v[116:119], v[166:169], v[204:207], v[116:119]
	v_mfma_f32_16x16x32_bf16 v[112:115], v[188:191], v[204:207], v[112:115]
	v_mfma_f32_16x16x32_bf16 v[100:103], v[166:169], v[212:215], v[100:103]
	v_mfma_f32_16x16x32_bf16 v[96:99], v[188:191], v[212:215], v[96:99]
	v_mfma_f32_16x16x32_bf16 v[68:71], v[166:169], v[220:223], v[68:71]
	v_mfma_f32_16x16x32_bf16 v[64:67], v[188:191], v[220:223], v[64:67]
	s_barrier
	s_add_i32 s59, s59, s35
	v_lshl_add_u64 v[160:161], s[66:67], 0, v[148:149]
	s_mov_b32 m0, s59
	ds_read_b128 v[192:195], v165 offset:16384
	ds_read_b128 v[196:199], v165 offset:17408
	ds_read_b128 v[200:203], v165 offset:18432
	ds_read_b128 v[204:207], v165 offset:19456
	ds_read_b128 v[208:211], v165 offset:20480
	ds_read_b128 v[212:215], v165 offset:21504
	ds_read_b128 v[216:219], v165 offset:22528
	ds_read_b128 v[220:223], v165 offset:23552
	global_load_lds_dwordx4 v[160:161], off
	s_add_i32 m0, s59, 0x2000
	v_lshl_add_u64 v[174:175], s[66:67], 0, v[144:145]
	s_add_u32 s66, s66, s12
	s_addc_u32 s67, s67, s13
	s_add_i32 s44, s44, s35
	global_load_lds_dwordx4 v[174:175], off
	v_lshl_add_u64 v[238:239], s[66:67], 0, v[148:149]
	s_mov_b32 m0, s44
	v_lshl_add_u64 v[240:241], s[66:67], 0, v[144:145]
	global_load_lds_dwordx4 v[238:239], off
	s_add_i32 m0, s44, 0x2000
	v_lshl_add_u64 v[242:243], s[0:1], 0, v[150:151]
	global_load_lds_dwordx4 v[240:241], off
	s_mov_b32 m0, s36
	v_lshl_add_u64 v[244:245], s[0:1], 0, v[146:147]
	global_load_lds_dwordx4 v[242:243], off
	s_mov_b32 m0, s37
	s_nop 0
	global_load_lds_dwordx4 v[244:245], off
	s_waitcnt vmcnt(8)
	s_waitcnt lgkmcnt(0)
	s_barrier
	s_waitcnt lgkmcnt(0)
	v_mfma_f32_16x16x32_bf16 v[60:63], v[72:75], v[192:195], v[60:63]
	v_mfma_f32_16x16x32_bf16 v[56:59], v[80:83], v[192:195], v[56:59]
	v_mfma_f32_16x16x32_bf16 v[44:47], v[72:75], v[200:203], v[44:47]
	v_mfma_f32_16x16x32_bf16 v[40:43], v[80:83], v[200:203], v[40:43]
	v_mfma_f32_16x16x32_bf16 v[28:31], v[72:75], v[208:211], v[28:31]
	v_mfma_f32_16x16x32_bf16 v[24:27], v[80:83], v[208:211], v[24:27]
	v_mfma_f32_16x16x32_bf16 v[12:15], v[72:75], v[216:219], v[12:15]
	v_mfma_f32_16x16x32_bf16 v[8:11], v[80:83], v[216:219], v[8:11]
	v_mfma_f32_16x16x32_bf16 v[60:63], v[76:79], v[196:199], v[60:63]
	v_mfma_f32_16x16x32_bf16 v[56:59], v[92:95], v[196:199], v[56:59]
	v_mfma_f32_16x16x32_bf16 v[44:47], v[76:79], v[204:207], v[44:47]
	v_mfma_f32_16x16x32_bf16 v[40:43], v[92:95], v[204:207], v[40:43]
	v_mfma_f32_16x16x32_bf16 v[28:31], v[76:79], v[212:215], v[28:31]
	v_mfma_f32_16x16x32_bf16 v[24:27], v[92:95], v[212:215], v[24:27]
	v_mfma_f32_16x16x32_bf16 v[12:15], v[76:79], v[220:223], v[12:15]
	v_mfma_f32_16x16x32_bf16 v[8:11], v[92:95], v[220:223], v[8:11]
	v_mfma_f32_16x16x32_bf16 v[52:55], v[156:159], v[192:195], v[52:55]
	v_mfma_f32_16x16x32_bf16 v[48:51], v[170:173], v[192:195], v[48:51]
	v_mfma_f32_16x16x32_bf16 v[36:39], v[156:159], v[200:203], v[36:39]
	v_mfma_f32_16x16x32_bf16 v[32:35], v[170:173], v[200:203], v[32:35]
	v_mfma_f32_16x16x32_bf16 v[20:23], v[156:159], v[208:211], v[20:23]
	v_mfma_f32_16x16x32_bf16 v[16:19], v[170:173], v[208:211], v[16:19]
	v_mfma_f32_16x16x32_bf16 v[4:7], v[156:159], v[216:219], v[4:7]
	v_mfma_f32_16x16x32_bf16 v[0:3], v[170:173], v[216:219], v[0:3]
	v_mfma_f32_16x16x32_bf16 v[52:55], v[166:169], v[196:199], v[52:55]
	v_mfma_f32_16x16x32_bf16 v[48:51], v[188:191], v[196:199], v[48:51]
	v_mfma_f32_16x16x32_bf16 v[36:39], v[166:169], v[204:207], v[36:39]
	v_mfma_f32_16x16x32_bf16 v[32:35], v[188:191], v[204:207], v[32:35]
	v_mfma_f32_16x16x32_bf16 v[20:23], v[166:169], v[212:215], v[20:23]
	v_mfma_f32_16x16x32_bf16 v[16:19], v[188:191], v[212:215], v[16:19]
	v_mfma_f32_16x16x32_bf16 v[4:7], v[166:169], v[220:223], v[4:7]
	v_mfma_f32_16x16x32_bf16 v[0:3], v[188:191], v[220:223], v[0:3]
	s_barrier
	s_add_i32 s44, 0, 0x18000
	s_add_i32 s59, 0, 0x1c000
	v_add_u32_e32 v92, s44, v163
	v_add_u32_e32 v176, s59, v163
	ds_read_b128 v[72:75], v92
	ds_read_b128 v[76:79], v92 offset:1024
	ds_read_b128 v[80:83], v92 offset:2048
	ds_read_b128 v[92:95], v92 offset:3072
	ds_read_b128 v[156:159], v176
	ds_read_b128 v[166:169], v176 offset:1024
	ds_read_b128 v[170:173], v176 offset:2048
	ds_read_b128 v[188:191], v176 offset:3072
	s_add_u32 s0, s0, 0x10000
	s_addc_u32 s1, s1, 0
	s_mov_b32 m0, s40
	v_lshl_add_u64 v[246:247], s[0:1], 0, v[150:151]
	ds_read_b128 v[192:195], v165 offset:32768
	ds_read_b128 v[196:199], v165 offset:33792
	ds_read_b128 v[200:203], v165 offset:34816
	ds_read_b128 v[204:207], v165 offset:35840
	ds_read_b128 v[208:211], v165 offset:36864
	ds_read_b128 v[212:215], v165 offset:37888
	ds_read_b128 v[216:219], v165 offset:38912
	ds_read_b128 v[220:223], v165 offset:39936
	global_load_lds_dwordx4 v[246:247], off
	v_lshl_add_u64 v[246:247], s[0:1], 0, v[146:147]
	s_mov_b32 m0, s41
	s_nop 0
	global_load_lds_dwordx4 v[246:247], off
	s_waitcnt vmcnt(8)
	s_waitcnt lgkmcnt(0)
	s_barrier
	s_waitcnt lgkmcnt(0)
	v_mfma_f32_16x16x32_bf16 v[140:143], v[72:75], v[192:195], v[140:143]
	v_mfma_f32_16x16x32_bf16 v[136:139], v[80:83], v[192:195], v[136:139]
	v_mfma_f32_16x16x32_bf16 v[124:127], v[72:75], v[200:203], v[124:127]
	v_mfma_f32_16x16x32_bf16 v[120:123], v[80:83], v[200:203], v[120:123]
	v_mfma_f32_16x16x32_bf16 v[108:111], v[72:75], v[208:211], v[108:111]
	v_mfma_f32_16x16x32_bf16 v[104:107], v[80:83], v[208:211], v[104:107]
	v_mfma_f32_16x16x32_bf16 v[88:91], v[72:75], v[216:219], v[88:91]
	v_mfma_f32_16x16x32_bf16 v[84:87], v[80:83], v[216:219], v[84:87]
	v_mfma_f32_16x16x32_bf16 v[140:143], v[76:79], v[196:199], v[140:143]
	v_mfma_f32_16x16x32_bf16 v[136:139], v[92:95], v[196:199], v[136:139]
	v_mfma_f32_16x16x32_bf16 v[124:127], v[76:79], v[204:207], v[124:127]
	v_mfma_f32_16x16x32_bf16 v[120:123], v[92:95], v[204:207], v[120:123]
	v_mfma_f32_16x16x32_bf16 v[108:111], v[76:79], v[212:215], v[108:111]
	v_mfma_f32_16x16x32_bf16 v[104:107], v[92:95], v[212:215], v[104:107]
	v_mfma_f32_16x16x32_bf16 v[88:91], v[76:79], v[220:223], v[88:91]
	v_mfma_f32_16x16x32_bf16 v[84:87], v[92:95], v[220:223], v[84:87]
	v_mfma_f32_16x16x32_bf16 v[132:135], v[156:159], v[192:195], v[132:135]
	v_mfma_f32_16x16x32_bf16 v[128:131], v[170:173], v[192:195], v[128:131]
	v_mfma_f32_16x16x32_bf16 v[116:119], v[156:159], v[200:203], v[116:119]
	v_mfma_f32_16x16x32_bf16 v[112:115], v[170:173], v[200:203], v[112:115]
	v_mfma_f32_16x16x32_bf16 v[100:103], v[156:159], v[208:211], v[100:103]
	v_mfma_f32_16x16x32_bf16 v[96:99], v[170:173], v[208:211], v[96:99]
	v_mfma_f32_16x16x32_bf16 v[68:71], v[156:159], v[216:219], v[68:71]
	v_mfma_f32_16x16x32_bf16 v[64:67], v[170:173], v[216:219], v[64:67]
	v_mfma_f32_16x16x32_bf16 v[132:135], v[166:169], v[196:199], v[132:135]
	v_mfma_f32_16x16x32_bf16 v[128:131], v[188:191], v[196:199], v[128:131]
	v_mfma_f32_16x16x32_bf16 v[116:119], v[166:169], v[204:207], v[116:119]
	v_mfma_f32_16x16x32_bf16 v[112:115], v[188:191], v[204:207], v[112:115]
	v_mfma_f32_16x16x32_bf16 v[100:103], v[166:169], v[212:215], v[100:103]
	v_mfma_f32_16x16x32_bf16 v[96:99], v[188:191], v[212:215], v[96:99]
	v_mfma_f32_16x16x32_bf16 v[68:71], v[166:169], v[220:223], v[68:71]
	v_mfma_f32_16x16x32_bf16 v[64:67], v[188:191], v[220:223], v[64:67]
	s_barrier
	s_add_i32 s0, s44, s35
	v_lshl_add_u64 v[160:161], v[160:161], 0, s[96:97]
	s_mov_b32 m0, s0
	ds_read_b128 v[192:195], v165 offset:49152
	ds_read_b128 v[196:199], v165 offset:50176
	ds_read_b128 v[200:203], v165 offset:51200
	ds_read_b128 v[204:207], v165 offset:52224
	ds_read_b128 v[208:211], v165 offset:53248
	ds_read_b128 v[212:215], v165 offset:54272
	ds_read_b128 v[216:219], v165 offset:55296
	ds_read_b128 v[220:223], v165 offset:56320
	global_load_lds_dwordx4 v[160:161], off
	v_lshl_add_u64 v[160:161], v[174:175], 0, s[96:97]
	s_add_i32 m0, s0, 0x2000
	s_add_i32 s0, s59, s35
	global_load_lds_dwordx4 v[160:161], off
	v_lshl_add_u64 v[160:161], v[238:239], 0, s[96:97]
	s_mov_b32 m0, s0
	s_nop 0
	global_load_lds_dwordx4 v[160:161], off
	v_lshl_add_u64 v[160:161], v[240:241], 0, s[96:97]
	s_add_i32 m0, s0, 0x2000
	s_nop 0
	global_load_lds_dwordx4 v[160:161], off
	v_lshl_add_u64 v[160:161], v[242:243], 0, s[96:97]
	s_mov_b32 m0, s47
	s_nop 0
	global_load_lds_dwordx4 v[160:161], off
	v_lshl_add_u64 v[160:161], v[244:245], 0, s[96:97]
	s_mov_b32 m0, s48
	s_nop 0
	global_load_lds_dwordx4 v[160:161], off
	s_waitcnt vmcnt(8)
	s_waitcnt lgkmcnt(0)
	s_barrier
	s_waitcnt lgkmcnt(0)
	v_mfma_f32_16x16x32_bf16 v[60:63], v[72:75], v[192:195], v[60:63]
	v_mfma_f32_16x16x32_bf16 v[56:59], v[80:83], v[192:195], v[56:59]
	v_mfma_f32_16x16x32_bf16 v[44:47], v[72:75], v[200:203], v[44:47]
	v_mfma_f32_16x16x32_bf16 v[40:43], v[80:83], v[200:203], v[40:43]
	v_mfma_f32_16x16x32_bf16 v[28:31], v[72:75], v[208:211], v[28:31]
	v_mfma_f32_16x16x32_bf16 v[24:27], v[80:83], v[208:211], v[24:27]
	v_mfma_f32_16x16x32_bf16 v[12:15], v[72:75], v[216:219], v[12:15]
	v_mfma_f32_16x16x32_bf16 v[8:11], v[80:83], v[216:219], v[8:11]
	v_mfma_f32_16x16x32_bf16 v[60:63], v[76:79], v[196:199], v[60:63]
	v_mfma_f32_16x16x32_bf16 v[56:59], v[92:95], v[196:199], v[56:59]
	v_mfma_f32_16x16x32_bf16 v[44:47], v[76:79], v[204:207], v[44:47]
	v_mfma_f32_16x16x32_bf16 v[40:43], v[92:95], v[204:207], v[40:43]
	v_mfma_f32_16x16x32_bf16 v[28:31], v[76:79], v[212:215], v[28:31]
	v_mfma_f32_16x16x32_bf16 v[24:27], v[92:95], v[212:215], v[24:27]
	v_mfma_f32_16x16x32_bf16 v[12:15], v[76:79], v[220:223], v[12:15]
	v_mfma_f32_16x16x32_bf16 v[8:11], v[92:95], v[220:223], v[8:11]
	v_mfma_f32_16x16x32_bf16 v[52:55], v[156:159], v[192:195], v[52:55]
	v_mfma_f32_16x16x32_bf16 v[48:51], v[170:173], v[192:195], v[48:51]
	v_mfma_f32_16x16x32_bf16 v[36:39], v[156:159], v[200:203], v[36:39]
	v_mfma_f32_16x16x32_bf16 v[32:35], v[170:173], v[200:203], v[32:35]
	v_mfma_f32_16x16x32_bf16 v[20:23], v[156:159], v[208:211], v[20:23]
	v_mfma_f32_16x16x32_bf16 v[16:19], v[170:173], v[208:211], v[16:19]
	v_mfma_f32_16x16x32_bf16 v[4:7], v[156:159], v[216:219], v[4:7]
	v_mfma_f32_16x16x32_bf16 v[0:3], v[170:173], v[216:219], v[0:3]
	v_mfma_f32_16x16x32_bf16 v[52:55], v[166:169], v[196:199], v[52:55]
	v_mfma_f32_16x16x32_bf16 v[48:51], v[188:191], v[196:199], v[48:51]
	v_mfma_f32_16x16x32_bf16 v[36:39], v[166:169], v[204:207], v[36:39]
	v_mfma_f32_16x16x32_bf16 v[32:35], v[188:191], v[204:207], v[32:35]
	v_mfma_f32_16x16x32_bf16 v[20:23], v[166:169], v[212:215], v[20:23]
	v_mfma_f32_16x16x32_bf16 v[16:19], v[188:191], v[212:215], v[16:19]
	v_mfma_f32_16x16x32_bf16 v[4:7], v[166:169], v[220:223], v[4:7]
	v_mfma_f32_16x16x32_bf16 v[0:3], v[188:191], v[220:223], v[0:3]
	s_barrier
	s_add_u32 s4, s4, 0x100
	s_addc_u32 s5, s5, 0
	s_add_u32 s6, s6, 0x100
	s_addc_u32 s7, s7, 0
	s_cmp_ge_i32 s45, s50
	s_mov_b32 s44, s45
	s_cbranch_scc0 .LBB0_378
	v_readlane_b32 s66, v254, 46
	v_readlane_b32 s67, v254, 47
	s_and_b64 vcc, exec, s[20:21]
	s_cbranch_vccnz .LBB0_381
	s_branch .LBB0_382

.LBB0_867:
	s_add_i32 s20, s0, 2
	s_add_u32 s21, s4, 0xfffc0080
	s_addc_u32 s1, s5, -1
	s_add_i32 s33, 0, 0x10000
	s_cmp_eq_u32 s24, s0
	s_cselect_b32 s1, s22, s1
	s_cselect_b32 s0, s23, s21
	s_cselect_b32 s35, s87, s7
	s_cselect_b32 s34, s86, s6
	s_add_i32 s21, 0, 0x14000
	v_add_u32_e32 v140, s33, v164
	v_add_u32_e32 v162, s21, v164
	ds_read_b128 v[128:131], v140
	ds_read_b128 v[132:135], v140 offset:1024
	ds_read_b128 v[136:139], v140 offset:2048
	ds_read_b128 v[140:143], v140 offset:3072
	ds_read_b128 v[166:169], v162
	ds_read_b128 v[170:173], v162 offset:1024
	ds_read_b128 v[188:191], v162 offset:2048
	ds_read_b128 v[192:195], v162 offset:3072
	v_lshl_add_u64 v[162:163], s[4:5], 0, v[158:159]
	s_add_i32 m0, s50, 0xc000
	ds_read_b128 v[196:199], v165
	ds_read_b128 v[200:203], v165 offset:1024
	ds_read_b128 v[204:207], v165 offset:2048
	ds_read_b128 v[208:211], v165 offset:3072
	ds_read_b128 v[212:215], v165 offset:4096
	ds_read_b128 v[216:219], v165 offset:5120
	ds_read_b128 v[220:223], v165 offset:6144
	ds_read_b128 v[242:245], v165 offset:7168
	global_load_lds_dwordx4 v[162:163], off
	v_lshl_add_u64 v[162:163], s[4:5], 0, v[160:161]
	s_add_i32 m0, s50, 0xe000
	s_nop 0
	global_load_lds_dwordx4 v[162:163], off
	s_waitcnt vmcnt(8)
	s_waitcnt lgkmcnt(0)
	s_barrier
	s_waitcnt lgkmcnt(0)
	v_mfma_f32_16x16x32_bf16 v[92:95], v[128:131], v[196:199], v[92:95]
	v_mfma_f32_16x16x32_bf16 v[88:91], v[136:139], v[196:199], v[88:91]
	v_mfma_f32_16x16x32_bf16 v[80:83], v[128:131], v[204:207], v[80:83]
	v_mfma_f32_16x16x32_bf16 v[76:79], v[136:139], v[204:207], v[76:79]
	v_mfma_f32_16x16x32_bf16 v[68:71], v[128:131], v[212:215], v[68:71]
	v_mfma_f32_16x16x32_bf16 v[64:67], v[136:139], v[212:215], v[64:67]
	v_mfma_f32_16x16x32_bf16 v[56:59], v[128:131], v[220:223], v[56:59]
	v_mfma_f32_16x16x32_bf16 v[52:55], v[136:139], v[220:223], v[52:55]
	v_mfma_f32_16x16x32_bf16 v[92:95], v[132:135], v[200:203], v[92:95]
	v_mfma_f32_16x16x32_bf16 v[88:91], v[140:143], v[200:203], v[88:91]
	v_mfma_f32_16x16x32_bf16 v[80:83], v[132:135], v[208:211], v[80:83]
	v_mfma_f32_16x16x32_bf16 v[76:79], v[140:143], v[208:211], v[76:79]
	v_mfma_f32_16x16x32_bf16 v[68:71], v[132:135], v[216:219], v[68:71]
	v_mfma_f32_16x16x32_bf16 v[64:67], v[140:143], v[216:219], v[64:67]
	v_mfma_f32_16x16x32_bf16 v[56:59], v[132:135], v[242:245], v[56:59]
	v_mfma_f32_16x16x32_bf16 v[52:55], v[140:143], v[242:245], v[52:55]
	v_mfma_f32_16x16x32_bf16 v[84:87], v[166:169], v[196:199], v[84:87]
	v_mfma_f32_16x16x32_bf16 v[124:127], v[188:191], v[196:199], v[124:127]
	v_mfma_f32_16x16x32_bf16 v[72:75], v[166:169], v[204:207], v[72:75]
	v_mfma_f32_16x16x32_bf16 v[120:123], v[188:191], v[204:207], v[120:123]
	v_mfma_f32_16x16x32_bf16 v[60:63], v[166:169], v[212:215], v[60:63]
	v_mfma_f32_16x16x32_bf16 v[116:119], v[188:191], v[212:215], v[116:119]
	v_mfma_f32_16x16x32_bf16 v[48:51], v[166:169], v[220:223], v[48:51]
	v_mfma_f32_16x16x32_bf16 v[112:115], v[188:191], v[220:223], v[112:115]
	v_mfma_f32_16x16x32_bf16 v[84:87], v[170:173], v[200:203], v[84:87]
	v_mfma_f32_16x16x32_bf16 v[124:127], v[192:195], v[200:203], v[124:127]
	v_mfma_f32_16x16x32_bf16 v[72:75], v[170:173], v[208:211], v[72:75]
	v_mfma_f32_16x16x32_bf16 v[120:123], v[192:195], v[208:211], v[120:123]
	v_mfma_f32_16x16x32_bf16 v[60:63], v[170:173], v[216:219], v[60:63]
	v_mfma_f32_16x16x32_bf16 v[116:119], v[192:195], v[216:219], v[116:119]
	v_mfma_f32_16x16x32_bf16 v[48:51], v[170:173], v[242:245], v[48:51]
	v_mfma_f32_16x16x32_bf16 v[112:115], v[192:195], v[242:245], v[112:115]
	s_barrier
	s_add_i32 s33, s33, s13
	v_lshl_add_u64 v[162:163], s[34:35], 0, v[148:149]
	s_mov_b32 m0, s33
	ds_read_b128 v[196:199], v165 offset:16384
	ds_read_b128 v[200:203], v165 offset:17408
	ds_read_b128 v[204:207], v165 offset:18432
	ds_read_b128 v[208:211], v165 offset:19456
	ds_read_b128 v[212:215], v165 offset:20480
	ds_read_b128 v[216:219], v165 offset:21504
	ds_read_b128 v[220:223], v165 offset:22528
	ds_read_b128 v[242:245], v165 offset:23552
	global_load_lds_dwordx4 v[162:163], off
	s_add_i32 m0, s33, 0x2000
	v_lshl_add_u64 v[174:175], s[34:35], 0, v[144:145]
	s_add_u32 s34, s34, s8
	s_addc_u32 s35, s35, s9
	s_add_i32 s21, s21, s13
	global_load_lds_dwordx4 v[174:175], off
	v_lshl_add_u64 v[246:247], s[34:35], 0, v[148:149]
	s_mov_b32 m0, s21
	v_lshl_add_u64 v[248:249], s[34:35], 0, v[144:145]
	global_load_lds_dwordx4 v[246:247], off
	s_add_i32 m0, s21, 0x2000
	v_lshl_add_u64 v[250:251], s[0:1], 0, v[150:151]
	global_load_lds_dwordx4 v[248:249], off
	s_mov_b32 m0, s50
	v_lshl_add_u64 v[238:239], s[0:1], 0, v[146:147]
	global_load_lds_dwordx4 v[250:251], off
	s_mov_b32 m0, s51
	s_nop 0
	global_load_lds_dwordx4 v[238:239], off
	s_waitcnt vmcnt(8)
	s_waitcnt lgkmcnt(0)
	s_barrier
	s_waitcnt lgkmcnt(0)
	v_mfma_f32_16x16x32_bf16 v[44:47], v[128:131], v[196:199], v[44:47]
	v_mfma_f32_16x16x32_bf16 v[40:43], v[136:139], v[196:199], v[40:43]
	v_mfma_f32_16x16x32_bf16 v[32:35], v[128:131], v[204:207], v[32:35]
	v_mfma_f32_16x16x32_bf16 v[28:31], v[136:139], v[204:207], v[28:31]
	v_mfma_f32_16x16x32_bf16 v[20:23], v[128:131], v[212:215], v[20:23]
	v_mfma_f32_16x16x32_bf16 v[16:19], v[136:139], v[212:215], v[16:19]
	v_mfma_f32_16x16x32_bf16 v[8:11], v[128:131], v[220:223], v[8:11]
	v_mfma_f32_16x16x32_bf16 v[4:7], v[136:139], v[220:223], v[4:7]
	v_mfma_f32_16x16x32_bf16 v[44:47], v[132:135], v[200:203], v[44:47]
	v_mfma_f32_16x16x32_bf16 v[40:43], v[140:143], v[200:203], v[40:43]
	v_mfma_f32_16x16x32_bf16 v[32:35], v[132:135], v[208:211], v[32:35]
	v_mfma_f32_16x16x32_bf16 v[28:31], v[140:143], v[208:211], v[28:31]
	v_mfma_f32_16x16x32_bf16 v[20:23], v[132:135], v[216:219], v[20:23]
	v_mfma_f32_16x16x32_bf16 v[16:19], v[140:143], v[216:219], v[16:19]
	v_mfma_f32_16x16x32_bf16 v[8:11], v[132:135], v[242:245], v[8:11]
	v_mfma_f32_16x16x32_bf16 v[4:7], v[140:143], v[242:245], v[4:7]
	v_mfma_f32_16x16x32_bf16 v[36:39], v[166:169], v[196:199], v[36:39]
	v_mfma_f32_16x16x32_bf16 v[108:111], v[188:191], v[196:199], v[108:111]
	v_mfma_f32_16x16x32_bf16 v[24:27], v[166:169], v[204:207], v[24:27]
	v_mfma_f32_16x16x32_bf16 v[104:107], v[188:191], v[204:207], v[104:107]
	v_mfma_f32_16x16x32_bf16 v[12:15], v[166:169], v[212:215], v[12:15]
	v_mfma_f32_16x16x32_bf16 v[100:103], v[188:191], v[212:215], v[100:103]
	v_mfma_f32_16x16x32_bf16 v[0:3], v[166:169], v[220:223], v[0:3]
	v_mfma_f32_16x16x32_bf16 v[96:99], v[188:191], v[220:223], v[96:99]
	v_mfma_f32_16x16x32_bf16 v[36:39], v[170:173], v[200:203], v[36:39]
	v_mfma_f32_16x16x32_bf16 v[108:111], v[192:195], v[200:203], v[108:111]
	v_mfma_f32_16x16x32_bf16 v[24:27], v[170:173], v[208:211], v[24:27]
	v_mfma_f32_16x16x32_bf16 v[104:107], v[192:195], v[208:211], v[104:107]
	v_mfma_f32_16x16x32_bf16 v[12:15], v[170:173], v[216:219], v[12:15]
	v_mfma_f32_16x16x32_bf16 v[100:103], v[192:195], v[216:219], v[100:103]
	v_mfma_f32_16x16x32_bf16 v[0:3], v[170:173], v[242:245], v[0:3]
	v_mfma_f32_16x16x32_bf16 v[96:99], v[192:195], v[242:245], v[96:99]
	s_barrier
	s_add_i32 s21, 0, 0x18000
	s_add_i32 s33, 0, 0x1c000
	v_add_u32_e32 v140, s21, v164
	v_add_u32_e32 v176, s33, v164
	ds_read_b128 v[128:131], v140
	ds_read_b128 v[132:135], v140 offset:1024
	ds_read_b128 v[136:139], v140 offset:2048
	ds_read_b128 v[140:143], v140 offset:3072
	ds_read_b128 v[166:169], v176
	ds_read_b128 v[170:173], v176 offset:1024
	ds_read_b128 v[188:191], v176 offset:2048
	ds_read_b128 v[192:195], v176 offset:3072
	s_add_u32 s0, s0, 0x40000
	s_addc_u32 s1, s1, 0
	s_mov_b32 m0, s47
	v_lshl_add_u64 v[240:241], s[0:1], 0, v[150:151]
	ds_read_b128 v[196:199], v165 offset:32768
	ds_read_b128 v[200:203], v165 offset:33792
	ds_read_b128 v[204:207], v165 offset:34816
	ds_read_b128 v[208:211], v165 offset:35840
	ds_read_b128 v[212:215], v165 offset:36864
	ds_read_b128 v[216:219], v165 offset:37888
	ds_read_b128 v[220:223], v165 offset:38912
	ds_read_b128 v[242:245], v165 offset:39936
	global_load_lds_dwordx4 v[240:241], off
	v_lshl_add_u64 v[240:241], s[0:1], 0, v[146:147]
	s_mov_b32 m0, s12
	s_nop 0
	global_load_lds_dwordx4 v[240:241], off
	s_waitcnt vmcnt(8)
	s_waitcnt lgkmcnt(0)
	s_barrier
	s_waitcnt lgkmcnt(0)
	v_mfma_f32_16x16x32_bf16 v[92:95], v[128:131], v[196:199], v[92:95]
	v_mfma_f32_16x16x32_bf16 v[88:91], v[136:139], v[196:199], v[88:91]
	v_mfma_f32_16x16x32_bf16 v[80:83], v[128:131], v[204:207], v[80:83]
	v_mfma_f32_16x16x32_bf16 v[76:79], v[136:139], v[204:207], v[76:79]
	v_mfma_f32_16x16x32_bf16 v[68:71], v[128:131], v[212:215], v[68:71]
	v_mfma_f32_16x16x32_bf16 v[64:67], v[136:139], v[212:215], v[64:67]
	v_mfma_f32_16x16x32_bf16 v[56:59], v[128:131], v[220:223], v[56:59]
	v_mfma_f32_16x16x32_bf16 v[52:55], v[136:139], v[220:223], v[52:55]
	v_mfma_f32_16x16x32_bf16 v[92:95], v[132:135], v[200:203], v[92:95]
	v_mfma_f32_16x16x32_bf16 v[88:91], v[140:143], v[200:203], v[88:91]
	v_mfma_f32_16x16x32_bf16 v[80:83], v[132:135], v[208:211], v[80:83]
	v_mfma_f32_16x16x32_bf16 v[76:79], v[140:143], v[208:211], v[76:79]
	v_mfma_f32_16x16x32_bf16 v[68:71], v[132:135], v[216:219], v[68:71]
	v_mfma_f32_16x16x32_bf16 v[64:67], v[140:143], v[216:219], v[64:67]
	v_mfma_f32_16x16x32_bf16 v[56:59], v[132:135], v[242:245], v[56:59]
	v_mfma_f32_16x16x32_bf16 v[52:55], v[140:143], v[242:245], v[52:55]
	v_mfma_f32_16x16x32_bf16 v[84:87], v[166:169], v[196:199], v[84:87]
	v_mfma_f32_16x16x32_bf16 v[124:127], v[188:191], v[196:199], v[124:127]
	v_mfma_f32_16x16x32_bf16 v[72:75], v[166:169], v[204:207], v[72:75]
	v_mfma_f32_16x16x32_bf16 v[120:123], v[188:191], v[204:207], v[120:123]
	v_mfma_f32_16x16x32_bf16 v[60:63], v[166:169], v[212:215], v[60:63]
	v_mfma_f32_16x16x32_bf16 v[116:119], v[188:191], v[212:215], v[116:119]
	v_mfma_f32_16x16x32_bf16 v[48:51], v[166:169], v[220:223], v[48:51]
	v_mfma_f32_16x16x32_bf16 v[112:115], v[188:191], v[220:223], v[112:115]
	v_mfma_f32_16x16x32_bf16 v[84:87], v[170:173], v[200:203], v[84:87]
	v_mfma_f32_16x16x32_bf16 v[124:127], v[192:195], v[200:203], v[124:127]
	v_mfma_f32_16x16x32_bf16 v[72:75], v[170:173], v[208:211], v[72:75]
	v_mfma_f32_16x16x32_bf16 v[120:123], v[192:195], v[208:211], v[120:123]
	v_mfma_f32_16x16x32_bf16 v[60:63], v[170:173], v[216:219], v[60:63]
	v_mfma_f32_16x16x32_bf16 v[116:119], v[192:195], v[216:219], v[116:119]
	v_mfma_f32_16x16x32_bf16 v[48:51], v[170:173], v[242:245], v[48:51]
	v_mfma_f32_16x16x32_bf16 v[112:115], v[192:195], v[242:245], v[112:115]
	s_barrier
	s_add_i32 s0, s21, s13
	v_lshl_add_u64 v[162:163], v[162:163], 0, s[96:97]
	s_mov_b32 m0, s0
	ds_read_b128 v[196:199], v165 offset:49152
	ds_read_b128 v[200:203], v165 offset:50176
	ds_read_b128 v[204:207], v165 offset:51200
	ds_read_b128 v[208:211], v165 offset:52224
	ds_read_b128 v[212:215], v165 offset:53248
	ds_read_b128 v[216:219], v165 offset:54272
	ds_read_b128 v[220:223], v165 offset:55296
	ds_read_b128 v[242:245], v165 offset:56320
	global_load_lds_dwordx4 v[162:163], off
	v_lshl_add_u64 v[162:163], v[174:175], 0, s[96:97]
	s_add_i32 m0, s0, 0x2000
	s_add_i32 s0, s33, s13
	global_load_lds_dwordx4 v[162:163], off
	v_lshl_add_u64 v[162:163], v[246:247], 0, s[96:97]
	s_mov_b32 m0, s0
	s_nop 0
	global_load_lds_dwordx4 v[162:163], off
	v_lshl_add_u64 v[162:163], v[248:249], 0, s[96:97]
	s_add_i32 m0, s0, 0x2000
	s_nop 0
	global_load_lds_dwordx4 v[162:163], off
	v_lshl_add_u64 v[162:163], v[250:251], 0, s[96:97]
	s_mov_b32 m0, s16
	s_nop 0
	global_load_lds_dwordx4 v[162:163], off
	v_lshl_add_u64 v[162:163], v[238:239], 0, s[96:97]
	s_mov_b32 m0, s17
	s_nop 0
	global_load_lds_dwordx4 v[162:163], off
	s_waitcnt vmcnt(8)
	s_waitcnt lgkmcnt(0)
	s_barrier
	s_waitcnt lgkmcnt(0)
	v_mfma_f32_16x16x32_bf16 v[44:47], v[128:131], v[196:199], v[44:47]
	v_mfma_f32_16x16x32_bf16 v[40:43], v[136:139], v[196:199], v[40:43]
	v_mfma_f32_16x16x32_bf16 v[32:35], v[128:131], v[204:207], v[32:35]
	v_mfma_f32_16x16x32_bf16 v[28:31], v[136:139], v[204:207], v[28:31]
	v_mfma_f32_16x16x32_bf16 v[20:23], v[128:131], v[212:215], v[20:23]
	v_mfma_f32_16x16x32_bf16 v[16:19], v[136:139], v[212:215], v[16:19]
	v_mfma_f32_16x16x32_bf16 v[8:11], v[128:131], v[220:223], v[8:11]
	v_mfma_f32_16x16x32_bf16 v[4:7], v[136:139], v[220:223], v[4:7]
	v_mfma_f32_16x16x32_bf16 v[44:47], v[132:135], v[200:203], v[44:47]
	v_mfma_f32_16x16x32_bf16 v[40:43], v[140:143], v[200:203], v[40:43]
	v_mfma_f32_16x16x32_bf16 v[32:35], v[132:135], v[208:211], v[32:35]
	v_mfma_f32_16x16x32_bf16 v[28:31], v[140:143], v[208:211], v[28:31]
	v_mfma_f32_16x16x32_bf16 v[20:23], v[132:135], v[216:219], v[20:23]
	v_mfma_f32_16x16x32_bf16 v[16:19], v[140:143], v[216:219], v[16:19]
	v_mfma_f32_16x16x32_bf16 v[8:11], v[132:135], v[242:245], v[8:11]
	v_mfma_f32_16x16x32_bf16 v[4:7], v[140:143], v[242:245], v[4:7]
	v_mfma_f32_16x16x32_bf16 v[36:39], v[166:169], v[196:199], v[36:39]
	v_mfma_f32_16x16x32_bf16 v[108:111], v[188:191], v[196:199], v[108:111]
	v_mfma_f32_16x16x32_bf16 v[24:27], v[166:169], v[204:207], v[24:27]
	v_mfma_f32_16x16x32_bf16 v[104:107], v[188:191], v[204:207], v[104:107]
	v_mfma_f32_16x16x32_bf16 v[12:15], v[166:169], v[212:215], v[12:15]
	v_mfma_f32_16x16x32_bf16 v[100:103], v[188:191], v[212:215], v[100:103]
	v_mfma_f32_16x16x32_bf16 v[0:3], v[166:169], v[220:223], v[0:3]
	v_mfma_f32_16x16x32_bf16 v[96:99], v[188:191], v[220:223], v[96:99]
	v_mfma_f32_16x16x32_bf16 v[36:39], v[170:173], v[200:203], v[36:39]
	v_mfma_f32_16x16x32_bf16 v[108:111], v[192:195], v[200:203], v[108:111]
	v_mfma_f32_16x16x32_bf16 v[24:27], v[170:173], v[208:211], v[24:27]
	v_mfma_f32_16x16x32_bf16 v[104:107], v[192:195], v[208:211], v[104:107]
	v_mfma_f32_16x16x32_bf16 v[12:15], v[170:173], v[216:219], v[12:15]
	v_mfma_f32_16x16x32_bf16 v[100:103], v[192:195], v[216:219], v[100:103]
	v_mfma_f32_16x16x32_bf16 v[0:3], v[170:173], v[242:245], v[0:3]
	v_mfma_f32_16x16x32_bf16 v[96:99], v[192:195], v[242:245], v[96:99]
	s_barrier
	s_add_u32 s4, s4, 0x100
	s_addc_u32 s5, s5, 0
	s_add_u32 s6, s6, 0x100
	s_addc_u32 s7, s7, 0
	s_cmp_ge_i32 s20, s25
	s_mov_b32 s0, s20
	s_cbranch_scc0 .LBB0_867
	v_mov_b32_e32 v250, v178
	s_and_b64 vcc, exec, s[28:29]
	s_cbranch_vccnz .LBB0_889

.LBB0_1046:
	s_add_i32 s47, s0, 2
	s_add_u32 s1, s20, 0xfffc0080
	s_addc_u32 s22, s21, -1
	s_add_i32 s48, 0, 0x10000
	s_cmp_eq_u32 s37, s0
	s_cselect_b32 s23, s11, s22
	s_cselect_b32 s22, s13, s1
	v_add_u32_e32 v143, s48, v141
	s_cselect_b32 s1, s19, s46
	s_cselect_b32 s0, s44, s45
	s_add_i32 s54, 0, 0x14000
	ds_read_b128 v[144:147], v143
	ds_read_b128 v[148:151], v143 offset:1024
	ds_read_b128 v[152:155], v143 offset:2048
	ds_read_b128 v[156:159], v143 offset:3072
	v_add_u32_e32 v143, s54, v141
	ds_read_b128 v[160:163], v143
	ds_read_b128 v[164:167], v143 offset:1024
	ds_read_b128 v[168:171], v143 offset:2048
	ds_read_b128 v[172:175], v143 offset:3072
	v_lshl_add_u64 v[220:221], s[20:21], 0, v[136:137]
	s_add_i32 m0, s29, 0xc000
	ds_read_b128 v[188:191], v142
	ds_read_b128 v[192:195], v142 offset:1024
	ds_read_b128 v[196:199], v142 offset:2048
	ds_read_b128 v[200:203], v142 offset:3072
	ds_read_b128 v[204:207], v142 offset:4096
	ds_read_b128 v[208:211], v142 offset:5120
	ds_read_b128 v[212:215], v142 offset:6144
	ds_read_b128 v[216:219], v142 offset:7168
	global_load_lds_dwordx4 v[220:221], off
	v_lshl_add_u64 v[220:221], s[20:21], 0, v[138:139]
	s_add_i32 m0, s29, 0xe000
	s_nop 0
	global_load_lds_dwordx4 v[220:221], off
	s_waitcnt vmcnt(8)
	s_waitcnt lgkmcnt(0)
	s_barrier
	s_waitcnt lgkmcnt(0)
	v_mfma_f32_16x16x32_bf16 v[124:127], v[144:147], v[188:191], v[124:127]
	v_mfma_f32_16x16x32_bf16 v[120:123], v[152:155], v[188:191], v[120:123]
	v_mfma_f32_16x16x32_bf16 v[108:111], v[144:147], v[196:199], v[108:111]
	v_mfma_f32_16x16x32_bf16 v[104:107], v[152:155], v[196:199], v[104:107]
	v_mfma_f32_16x16x32_bf16 v[92:95], v[144:147], v[204:207], v[92:95]
	v_mfma_f32_16x16x32_bf16 v[88:91], v[152:155], v[204:207], v[88:91]
	v_mfma_f32_16x16x32_bf16 v[76:79], v[144:147], v[212:215], v[76:79]
	v_mfma_f32_16x16x32_bf16 v[72:75], v[152:155], v[212:215], v[72:75]
	v_mfma_f32_16x16x32_bf16 v[124:127], v[148:151], v[192:195], v[124:127]
	v_mfma_f32_16x16x32_bf16 v[120:123], v[156:159], v[192:195], v[120:123]
	v_mfma_f32_16x16x32_bf16 v[108:111], v[148:151], v[200:203], v[108:111]
	v_mfma_f32_16x16x32_bf16 v[104:107], v[156:159], v[200:203], v[104:107]
	v_mfma_f32_16x16x32_bf16 v[92:95], v[148:151], v[208:211], v[92:95]
	v_mfma_f32_16x16x32_bf16 v[88:91], v[156:159], v[208:211], v[88:91]
	v_mfma_f32_16x16x32_bf16 v[76:79], v[148:151], v[216:219], v[76:79]
	v_mfma_f32_16x16x32_bf16 v[72:75], v[156:159], v[216:219], v[72:75]
	v_mfma_f32_16x16x32_bf16 v[116:119], v[160:163], v[188:191], v[116:119]
	v_mfma_f32_16x16x32_bf16 v[112:115], v[168:171], v[188:191], v[112:115]
	v_mfma_f32_16x16x32_bf16 v[100:103], v[160:163], v[196:199], v[100:103]
	v_mfma_f32_16x16x32_bf16 v[96:99], v[168:171], v[196:199], v[96:99]
	v_mfma_f32_16x16x32_bf16 v[84:87], v[160:163], v[204:207], v[84:87]
	v_mfma_f32_16x16x32_bf16 v[80:83], v[168:171], v[204:207], v[80:83]
	v_mfma_f32_16x16x32_bf16 v[68:71], v[160:163], v[212:215], v[68:71]
	v_mfma_f32_16x16x32_bf16 v[64:67], v[168:171], v[212:215], v[64:67]
	v_mfma_f32_16x16x32_bf16 v[116:119], v[164:167], v[192:195], v[116:119]
	v_mfma_f32_16x16x32_bf16 v[112:115], v[172:175], v[192:195], v[112:115]
	v_mfma_f32_16x16x32_bf16 v[100:103], v[164:167], v[200:203], v[100:103]
	v_mfma_f32_16x16x32_bf16 v[96:99], v[172:175], v[200:203], v[96:99]
	v_mfma_f32_16x16x32_bf16 v[84:87], v[164:167], v[208:211], v[84:87]
	v_mfma_f32_16x16x32_bf16 v[80:83], v[172:175], v[208:211], v[80:83]
	v_mfma_f32_16x16x32_bf16 v[68:71], v[164:167], v[216:219], v[68:71]
	v_mfma_f32_16x16x32_bf16 v[64:67], v[172:175], v[216:219], v[64:67]
	s_barrier
	s_add_i32 s48, s48, s28
	v_lshl_add_u64 v[220:221], s[0:1], 0, v[176:177]
	s_mov_b32 m0, s48
	ds_read_b128 v[188:191], v142 offset:16384
	ds_read_b128 v[192:195], v142 offset:17408
	ds_read_b128 v[196:199], v142 offset:18432
	ds_read_b128 v[200:203], v142 offset:19456
	ds_read_b128 v[204:207], v142 offset:20480
	ds_read_b128 v[208:211], v142 offset:21504
	ds_read_b128 v[212:215], v142 offset:22528
	ds_read_b128 v[216:219], v142 offset:23552
	global_load_lds_dwordx4 v[220:221], off
	s_add_i32 m0, s48, 0x2000
	s_add_u32 s50, s0, 0x80000
	v_lshl_add_u64 v[222:223], s[0:1], 0, v[128:129]
	s_addc_u32 s51, s1, 0
	s_add_i32 s48, s54, s28
	global_load_lds_dwordx4 v[222:223], off
	v_lshl_add_u64 v[242:243], s[50:51], 0, v[176:177]
	s_mov_b32 m0, s48
	v_lshl_add_u64 v[244:245], s[22:23], 0, v[130:131]
	global_load_lds_dwordx4 v[242:243], off
	v_lshl_add_u64 v[242:243], s[50:51], 0, v[128:129]
	s_add_i32 m0, s48, 0x2000
	s_nop 0
	global_load_lds_dwordx4 v[242:243], off
	v_lshl_add_u64 v[242:243], s[22:23], 0, v[132:133]
	s_mov_b32 m0, s29
	s_nop 0
	global_load_lds_dwordx4 v[242:243], off
	s_mov_b32 m0, s30
	s_nop 0
	global_load_lds_dwordx4 v[244:245], off
	s_waitcnt vmcnt(8)
	s_waitcnt lgkmcnt(0)
	s_barrier
	s_waitcnt lgkmcnt(0)
	v_mfma_f32_16x16x32_bf16 v[60:63], v[144:147], v[188:191], v[60:63]
	v_mfma_f32_16x16x32_bf16 v[56:59], v[152:155], v[188:191], v[56:59]
	v_mfma_f32_16x16x32_bf16 v[44:47], v[144:147], v[196:199], v[44:47]
	v_mfma_f32_16x16x32_bf16 v[40:43], v[152:155], v[196:199], v[40:43]
	v_mfma_f32_16x16x32_bf16 v[28:31], v[144:147], v[204:207], v[28:31]
	v_mfma_f32_16x16x32_bf16 v[24:27], v[152:155], v[204:207], v[24:27]
	v_mfma_f32_16x16x32_bf16 v[12:15], v[144:147], v[212:215], v[12:15]
	v_mfma_f32_16x16x32_bf16 v[8:11], v[152:155], v[212:215], v[8:11]
	v_mfma_f32_16x16x32_bf16 v[60:63], v[148:151], v[192:195], v[60:63]
	v_mfma_f32_16x16x32_bf16 v[56:59], v[156:159], v[192:195], v[56:59]
	v_mfma_f32_16x16x32_bf16 v[44:47], v[148:151], v[200:203], v[44:47]
	v_mfma_f32_16x16x32_bf16 v[40:43], v[156:159], v[200:203], v[40:43]
	v_mfma_f32_16x16x32_bf16 v[28:31], v[148:151], v[208:211], v[28:31]
	v_mfma_f32_16x16x32_bf16 v[24:27], v[156:159], v[208:211], v[24:27]
	v_mfma_f32_16x16x32_bf16 v[12:15], v[148:151], v[216:219], v[12:15]
	v_mfma_f32_16x16x32_bf16 v[8:11], v[156:159], v[216:219], v[8:11]
	v_mfma_f32_16x16x32_bf16 v[52:55], v[160:163], v[188:191], v[52:55]
	v_mfma_f32_16x16x32_bf16 v[48:51], v[168:171], v[188:191], v[48:51]
	v_mfma_f32_16x16x32_bf16 v[36:39], v[160:163], v[196:199], v[36:39]
	v_mfma_f32_16x16x32_bf16 v[32:35], v[168:171], v[196:199], v[32:35]
	v_mfma_f32_16x16x32_bf16 v[20:23], v[160:163], v[204:207], v[20:23]
	v_mfma_f32_16x16x32_bf16 v[16:19], v[168:171], v[204:207], v[16:19]
	v_mfma_f32_16x16x32_bf16 v[4:7], v[160:163], v[212:215], v[4:7]
	v_mfma_f32_16x16x32_bf16 v[0:3], v[168:171], v[212:215], v[0:3]
	v_mfma_f32_16x16x32_bf16 v[52:55], v[164:167], v[192:195], v[52:55]
	v_mfma_f32_16x16x32_bf16 v[48:51], v[172:175], v[192:195], v[48:51]
	v_mfma_f32_16x16x32_bf16 v[36:39], v[164:167], v[200:203], v[36:39]
	v_mfma_f32_16x16x32_bf16 v[32:35], v[172:175], v[200:203], v[32:35]
	v_mfma_f32_16x16x32_bf16 v[20:23], v[164:167], v[208:211], v[20:23]
	v_mfma_f32_16x16x32_bf16 v[16:19], v[172:175], v[208:211], v[16:19]
	v_mfma_f32_16x16x32_bf16 v[4:7], v[164:167], v[216:219], v[4:7]
	v_mfma_f32_16x16x32_bf16 v[0:3], v[172:175], v[216:219], v[0:3]
	s_barrier
	s_add_i32 s48, 0, 0x18000
	v_add_u32_e32 v143, s48, v141
	s_add_i32 s50, 0, 0x1c000
	ds_read_b128 v[144:147], v143
	ds_read_b128 v[148:151], v143 offset:1024
	ds_read_b128 v[152:155], v143 offset:2048
	ds_read_b128 v[156:159], v143 offset:3072
	v_add_u32_e32 v143, s50, v141
	ds_read_b128 v[160:163], v143
	ds_read_b128 v[164:167], v143 offset:1024
	ds_read_b128 v[168:171], v143 offset:2048
	ds_read_b128 v[172:175], v143 offset:3072
	s_add_u32 s22, s22, 0x40000
	s_addc_u32 s23, s23, 0
	s_mov_b32 m0, s31
	v_lshl_add_u64 v[246:247], s[22:23], 0, v[132:133]
	ds_read_b128 v[188:191], v142 offset:32768
	ds_read_b128 v[192:195], v142 offset:33792
	ds_read_b128 v[196:199], v142 offset:34816
	ds_read_b128 v[200:203], v142 offset:35840
	ds_read_b128 v[204:207], v142 offset:36864
	ds_read_b128 v[208:211], v142 offset:37888
	ds_read_b128 v[212:215], v142 offset:38912
	ds_read_b128 v[216:219], v142 offset:39936
	global_load_lds_dwordx4 v[246:247], off
	v_lshl_add_u64 v[246:247], s[22:23], 0, v[130:131]
	s_mov_b32 m0, s33
	s_nop 0
	global_load_lds_dwordx4 v[246:247], off
	s_waitcnt vmcnt(8)
	s_waitcnt lgkmcnt(0)
	s_barrier
	s_waitcnt lgkmcnt(0)
	v_mfma_f32_16x16x32_bf16 v[124:127], v[144:147], v[188:191], v[124:127]
	v_mfma_f32_16x16x32_bf16 v[120:123], v[152:155], v[188:191], v[120:123]
	v_mfma_f32_16x16x32_bf16 v[108:111], v[144:147], v[196:199], v[108:111]
	v_mfma_f32_16x16x32_bf16 v[104:107], v[152:155], v[196:199], v[104:107]
	v_mfma_f32_16x16x32_bf16 v[92:95], v[144:147], v[204:207], v[92:95]
	v_mfma_f32_16x16x32_bf16 v[88:91], v[152:155], v[204:207], v[88:91]
	v_mfma_f32_16x16x32_bf16 v[76:79], v[144:147], v[212:215], v[76:79]
	v_mfma_f32_16x16x32_bf16 v[72:75], v[152:155], v[212:215], v[72:75]
	v_mfma_f32_16x16x32_bf16 v[124:127], v[148:151], v[192:195], v[124:127]
	v_mfma_f32_16x16x32_bf16 v[120:123], v[156:159], v[192:195], v[120:123]
	v_mfma_f32_16x16x32_bf16 v[108:111], v[148:151], v[200:203], v[108:111]
	v_mfma_f32_16x16x32_bf16 v[104:107], v[156:159], v[200:203], v[104:107]
	v_mfma_f32_16x16x32_bf16 v[92:95], v[148:151], v[208:211], v[92:95]
	v_mfma_f32_16x16x32_bf16 v[88:91], v[156:159], v[208:211], v[88:91]
	v_mfma_f32_16x16x32_bf16 v[76:79], v[148:151], v[216:219], v[76:79]
	v_mfma_f32_16x16x32_bf16 v[72:75], v[156:159], v[216:219], v[72:75]
	v_mfma_f32_16x16x32_bf16 v[116:119], v[160:163], v[188:191], v[116:119]
	v_mfma_f32_16x16x32_bf16 v[112:115], v[168:171], v[188:191], v[112:115]
	v_mfma_f32_16x16x32_bf16 v[100:103], v[160:163], v[196:199], v[100:103]
	v_mfma_f32_16x16x32_bf16 v[96:99], v[168:171], v[196:199], v[96:99]
	v_mfma_f32_16x16x32_bf16 v[84:87], v[160:163], v[204:207], v[84:87]
	v_mfma_f32_16x16x32_bf16 v[80:83], v[168:171], v[204:207], v[80:83]
	v_mfma_f32_16x16x32_bf16 v[68:71], v[160:163], v[212:215], v[68:71]
	v_mfma_f32_16x16x32_bf16 v[64:67], v[168:171], v[212:215], v[64:67]
	v_mfma_f32_16x16x32_bf16 v[116:119], v[164:167], v[192:195], v[116:119]
	v_mfma_f32_16x16x32_bf16 v[112:115], v[172:175], v[192:195], v[112:115]
	v_mfma_f32_16x16x32_bf16 v[100:103], v[164:167], v[200:203], v[100:103]
	v_mfma_f32_16x16x32_bf16 v[96:99], v[172:175], v[200:203], v[96:99]
	v_mfma_f32_16x16x32_bf16 v[84:87], v[164:167], v[208:211], v[84:87]
	v_mfma_f32_16x16x32_bf16 v[80:83], v[172:175], v[208:211], v[80:83]
	v_mfma_f32_16x16x32_bf16 v[68:71], v[164:167], v[216:219], v[68:71]
	v_mfma_f32_16x16x32_bf16 v[64:67], v[172:175], v[216:219], v[64:67]
	s_barrier
	s_add_i32 s22, s48, s28
	v_lshl_add_u64 v[220:221], v[220:221], 0, s[96:97]
	s_mov_b32 m0, s22
	ds_read_b128 v[188:191], v142 offset:49152
	ds_read_b128 v[192:195], v142 offset:50176
	ds_read_b128 v[196:199], v142 offset:51200
	ds_read_b128 v[200:203], v142 offset:52224
	ds_read_b128 v[204:207], v142 offset:53248
	ds_read_b128 v[208:211], v142 offset:54272
	ds_read_b128 v[212:215], v142 offset:55296
	ds_read_b128 v[216:219], v142 offset:56320
	global_load_lds_dwordx4 v[220:221], off
	s_add_i32 m0, s22, 0x2000
	s_add_u32 s0, s0, 0x80080
	v_lshl_add_u64 v[220:221], v[222:223], 0, s[96:97]
	s_addc_u32 s1, s1, 0
	s_add_i32 s22, s50, s28
	global_load_lds_dwordx4 v[220:221], off
	v_lshl_add_u64 v[220:221], s[0:1], 0, v[176:177]
	s_mov_b32 m0, s22
	s_nop 0
	global_load_lds_dwordx4 v[220:221], off
	v_lshl_add_u64 v[220:221], s[0:1], 0, v[128:129]
	s_add_i32 m0, s22, 0x2000
	s_nop 0
	global_load_lds_dwordx4 v[220:221], off
	v_lshl_add_u64 v[220:221], v[242:243], 0, s[96:97]
	s_mov_b32 m0, s35
	s_nop 0
	global_load_lds_dwordx4 v[220:221], off
	v_lshl_add_u64 v[220:221], v[244:245], 0, s[96:97]
	s_mov_b32 m0, s36
	s_nop 0
	global_load_lds_dwordx4 v[220:221], off
	s_waitcnt vmcnt(8)
	s_waitcnt lgkmcnt(0)
	s_barrier
	s_waitcnt lgkmcnt(0)
	v_mfma_f32_16x16x32_bf16 v[60:63], v[144:147], v[188:191], v[60:63]
	v_mfma_f32_16x16x32_bf16 v[56:59], v[152:155], v[188:191], v[56:59]
	v_mfma_f32_16x16x32_bf16 v[44:47], v[144:147], v[196:199], v[44:47]
	v_mfma_f32_16x16x32_bf16 v[40:43], v[152:155], v[196:199], v[40:43]
	v_mfma_f32_16x16x32_bf16 v[28:31], v[144:147], v[204:207], v[28:31]
	v_mfma_f32_16x16x32_bf16 v[24:27], v[152:155], v[204:207], v[24:27]
	v_mfma_f32_16x16x32_bf16 v[12:15], v[144:147], v[212:215], v[12:15]
	v_mfma_f32_16x16x32_bf16 v[8:11], v[152:155], v[212:215], v[8:11]
	v_mfma_f32_16x16x32_bf16 v[60:63], v[148:151], v[192:195], v[60:63]
	v_mfma_f32_16x16x32_bf16 v[56:59], v[156:159], v[192:195], v[56:59]
	v_mfma_f32_16x16x32_bf16 v[44:47], v[148:151], v[200:203], v[44:47]
	v_mfma_f32_16x16x32_bf16 v[40:43], v[156:159], v[200:203], v[40:43]
	v_mfma_f32_16x16x32_bf16 v[28:31], v[148:151], v[208:211], v[28:31]
	v_mfma_f32_16x16x32_bf16 v[24:27], v[156:159], v[208:211], v[24:27]
	v_mfma_f32_16x16x32_bf16 v[12:15], v[148:151], v[216:219], v[12:15]
	v_mfma_f32_16x16x32_bf16 v[8:11], v[156:159], v[216:219], v[8:11]
	v_mfma_f32_16x16x32_bf16 v[52:55], v[160:163], v[188:191], v[52:55]
	v_mfma_f32_16x16x32_bf16 v[48:51], v[168:171], v[188:191], v[48:51]
	v_mfma_f32_16x16x32_bf16 v[36:39], v[160:163], v[196:199], v[36:39]
	v_mfma_f32_16x16x32_bf16 v[32:35], v[168:171], v[196:199], v[32:35]
	v_mfma_f32_16x16x32_bf16 v[20:23], v[160:163], v[204:207], v[20:23]
	v_mfma_f32_16x16x32_bf16 v[16:19], v[168:171], v[204:207], v[16:19]
	v_mfma_f32_16x16x32_bf16 v[4:7], v[160:163], v[212:215], v[4:7]
	v_mfma_f32_16x16x32_bf16 v[0:3], v[168:171], v[212:215], v[0:3]
	v_mfma_f32_16x16x32_bf16 v[52:55], v[164:167], v[192:195], v[52:55]
	v_mfma_f32_16x16x32_bf16 v[48:51], v[172:175], v[192:195], v[48:51]
	v_mfma_f32_16x16x32_bf16 v[36:39], v[164:167], v[200:203], v[36:39]
	v_mfma_f32_16x16x32_bf16 v[32:35], v[172:175], v[200:203], v[32:35]
	v_mfma_f32_16x16x32_bf16 v[20:23], v[164:167], v[208:211], v[20:23]
	v_mfma_f32_16x16x32_bf16 v[16:19], v[172:175], v[208:211], v[16:19]
	v_mfma_f32_16x16x32_bf16 v[4:7], v[164:167], v[216:219], v[4:7]
	v_mfma_f32_16x16x32_bf16 v[0:3], v[172:175], v[216:219], v[0:3]
	s_barrier
	s_add_u32 s20, s20, 0x100
	s_addc_u32 s21, s21, 0
	s_add_u32 s45, s45, 0x100
	s_addc_u32 s46, s46, 0
	s_cmp_ge_i32 s47, s34
	s_mov_b32 s0, s47
	s_cbranch_scc0 .LBB0_1046

.LBB0_1397:
	s_add_i32 s88, s66, 2
	s_add_u32 s89, s6, 0xfffc0080
	s_addc_u32 s67, s7, -1
	s_add_i32 s0, 0, 0x10000
	s_cmp_eq_u32 s46, s66
	s_cselect_b32 s67, s3, s67
	s_cselect_b32 s66, s2, s89
	s_cselect_b32 vcc_hi, s55, s87
	s_cselect_b32 vcc_lo, s54, s65
	s_add_i32 s1, 0, 0x14000
	v_add_u32_e32 v108, s0, v242
	v_add_u32_e32 v156, s1, v242
	ds_read_b128 v[96:99], v108
	ds_read_b128 v[100:103], v108 offset:1024
	ds_read_b128 v[104:107], v108 offset:2048
	ds_read_b128 v[108:111], v108 offset:3072
	ds_read_b128 v[144:147], v156
	ds_read_b128 v[148:151], v156 offset:1024
	ds_read_b128 v[152:155], v156 offset:2048
	ds_read_b128 v[156:159], v156 offset:3072
	v_lshl_add_u64 v[214:215], s[6:7], 0, v[194:195]
	s_add_i32 m0, s31, 0xc000
	ds_read_b128 v[160:163], v244
	ds_read_b128 v[164:167], v244 offset:1024
	ds_read_b128 v[168:171], v244 offset:2048
	ds_read_b128 v[172:175], v244 offset:3072
	ds_read_b128 v[198:201], v244 offset:4096
	ds_read_b128 v[202:205], v244 offset:5120
	ds_read_b128 v[206:209], v244 offset:6144
	ds_read_b128 v[210:213], v244 offset:7168
	global_load_lds_dwordx4 v[214:215], off
	v_lshl_add_u64 v[214:215], s[6:7], 0, v[196:197]
	s_add_i32 m0, s31, 0xe000
	s_nop 0
	global_load_lds_dwordx4 v[214:215], off
	s_waitcnt vmcnt(8)
	s_waitcnt lgkmcnt(0)
	s_barrier
	s_waitcnt lgkmcnt(0)
	v_mfma_f32_16x16x32_bf16 v[136:139], v[96:99], v[160:163], v[136:139]
	v_mfma_f32_16x16x32_bf16 v[140:143], v[104:107], v[160:163], v[140:143]
	v_mfma_f32_16x16x32_bf16 v[124:127], v[96:99], v[168:171], v[124:127]
	v_mfma_f32_16x16x32_bf16 v[120:123], v[104:107], v[168:171], v[120:123]
	v_mfma_f32_16x16x32_bf16 v[92:95], v[96:99], v[198:201], v[92:95]
	v_mfma_f32_16x16x32_bf16 v[88:91], v[104:107], v[198:201], v[88:91]
	v_mfma_f32_16x16x32_bf16 v[76:79], v[96:99], v[206:209], v[76:79]
	v_mfma_f32_16x16x32_bf16 v[72:75], v[104:107], v[206:209], v[72:75]
	v_mfma_f32_16x16x32_bf16 v[136:139], v[100:103], v[164:167], v[136:139]
	v_mfma_f32_16x16x32_bf16 v[140:143], v[108:111], v[164:167], v[140:143]
	v_mfma_f32_16x16x32_bf16 v[124:127], v[100:103], v[172:175], v[124:127]
	v_mfma_f32_16x16x32_bf16 v[120:123], v[108:111], v[172:175], v[120:123]
	v_mfma_f32_16x16x32_bf16 v[92:95], v[100:103], v[202:205], v[92:95]
	v_mfma_f32_16x16x32_bf16 v[88:91], v[108:111], v[202:205], v[88:91]
	v_mfma_f32_16x16x32_bf16 v[76:79], v[100:103], v[210:213], v[76:79]
	v_mfma_f32_16x16x32_bf16 v[72:75], v[108:111], v[210:213], v[72:75]
	v_mfma_f32_16x16x32_bf16 v[132:135], v[144:147], v[160:163], v[132:135]
	v_mfma_f32_16x16x32_bf16 v[128:131], v[152:155], v[160:163], v[128:131]
	v_mfma_f32_16x16x32_bf16 v[116:119], v[144:147], v[168:171], v[116:119]
	v_mfma_f32_16x16x32_bf16 v[112:115], v[152:155], v[168:171], v[112:115]
	v_mfma_f32_16x16x32_bf16 v[84:87], v[144:147], v[198:201], v[84:87]
	v_mfma_f32_16x16x32_bf16 v[80:83], v[152:155], v[198:201], v[80:83]
	v_mfma_f32_16x16x32_bf16 v[68:71], v[144:147], v[206:209], v[68:71]
	v_mfma_f32_16x16x32_bf16 v[64:67], v[152:155], v[206:209], v[64:67]
	v_mfma_f32_16x16x32_bf16 v[132:135], v[148:151], v[164:167], v[132:135]
	v_mfma_f32_16x16x32_bf16 v[128:131], v[156:159], v[164:167], v[128:131]
	v_mfma_f32_16x16x32_bf16 v[116:119], v[148:151], v[172:175], v[116:119]
	v_mfma_f32_16x16x32_bf16 v[112:115], v[156:159], v[172:175], v[112:115]
	v_mfma_f32_16x16x32_bf16 v[84:87], v[148:151], v[202:205], v[84:87]
	v_mfma_f32_16x16x32_bf16 v[80:83], v[156:159], v[202:205], v[80:83]
	v_mfma_f32_16x16x32_bf16 v[68:71], v[148:151], v[210:213], v[68:71]
	v_mfma_f32_16x16x32_bf16 v[64:67], v[156:159], v[210:213], v[64:67]
	s_barrier
	s_add_i32 s0, s0, s30
	v_lshl_add_u64 v[214:215], vcc, 0, v[176:177]
	s_mov_b32 m0, s0
	ds_read_b128 v[160:163], v244 offset:16384
	ds_read_b128 v[164:167], v244 offset:17408
	ds_read_b128 v[168:171], v244 offset:18432
	ds_read_b128 v[172:175], v244 offset:19456
	ds_read_b128 v[198:201], v244 offset:20480
	ds_read_b128 v[202:205], v244 offset:21504
	ds_read_b128 v[206:209], v244 offset:22528
	ds_read_b128 v[210:213], v244 offset:23552
	global_load_lds_dwordx4 v[214:215], off
	s_add_i32 m0, s0, 0x2000
	v_lshl_add_u64 v[216:217], vcc, 0, v[188:189]
	s_add_u32 vcc_lo, vcc_lo, s22
	s_addc_u32 vcc_hi, vcc_hi, s23
	s_add_i32 s0, s1, s30
	global_load_lds_dwordx4 v[216:217], off
	v_lshl_add_u64 v[218:219], vcc, 0, v[176:177]
	s_mov_b32 m0, s0
	v_lshl_add_u64 v[220:221], vcc, 0, v[188:189]
	global_load_lds_dwordx4 v[218:219], off
	s_add_i32 m0, s0, 0x2000
	v_lshl_add_u64 v[222:223], s[66:67], 0, v[192:193]
	global_load_lds_dwordx4 v[220:221], off
	s_mov_b32 m0, s31
	v_lshl_add_u64 v[238:239], s[66:67], 0, v[190:191]
	global_load_lds_dwordx4 v[222:223], off
	s_mov_b32 m0, s33
	s_nop 0
	global_load_lds_dwordx4 v[238:239], off
	s_waitcnt vmcnt(8)
	s_waitcnt lgkmcnt(0)
	s_barrier
	s_waitcnt lgkmcnt(0)
	v_mfma_f32_16x16x32_bf16 v[60:63], v[96:99], v[160:163], v[60:63]
	v_mfma_f32_16x16x32_bf16 v[56:59], v[104:107], v[160:163], v[56:59]
	v_mfma_f32_16x16x32_bf16 v[44:47], v[96:99], v[168:171], v[44:47]
	v_mfma_f32_16x16x32_bf16 v[40:43], v[104:107], v[168:171], v[40:43]
	v_mfma_f32_16x16x32_bf16 v[28:31], v[96:99], v[198:201], v[28:31]
	v_mfma_f32_16x16x32_bf16 v[24:27], v[104:107], v[198:201], v[24:27]
	v_mfma_f32_16x16x32_bf16 v[12:15], v[96:99], v[206:209], v[12:15]
	v_mfma_f32_16x16x32_bf16 v[8:11], v[104:107], v[206:209], v[8:11]
	v_mfma_f32_16x16x32_bf16 v[60:63], v[100:103], v[164:167], v[60:63]
	v_mfma_f32_16x16x32_bf16 v[56:59], v[108:111], v[164:167], v[56:59]
	v_mfma_f32_16x16x32_bf16 v[44:47], v[100:103], v[172:175], v[44:47]
	v_mfma_f32_16x16x32_bf16 v[40:43], v[108:111], v[172:175], v[40:43]
	v_mfma_f32_16x16x32_bf16 v[28:31], v[100:103], v[202:205], v[28:31]
	v_mfma_f32_16x16x32_bf16 v[24:27], v[108:111], v[202:205], v[24:27]
	v_mfma_f32_16x16x32_bf16 v[12:15], v[100:103], v[210:213], v[12:15]
	v_mfma_f32_16x16x32_bf16 v[8:11], v[108:111], v[210:213], v[8:11]
	v_mfma_f32_16x16x32_bf16 v[52:55], v[144:147], v[160:163], v[52:55]
	v_mfma_f32_16x16x32_bf16 v[48:51], v[152:155], v[160:163], v[48:51]
	v_mfma_f32_16x16x32_bf16 v[36:39], v[144:147], v[168:171], v[36:39]
	v_mfma_f32_16x16x32_bf16 v[32:35], v[152:155], v[168:171], v[32:35]
	v_mfma_f32_16x16x32_bf16 v[20:23], v[144:147], v[198:201], v[20:23]
	v_mfma_f32_16x16x32_bf16 v[16:19], v[152:155], v[198:201], v[16:19]
	v_mfma_f32_16x16x32_bf16 v[4:7], v[144:147], v[206:209], v[4:7]
	v_mfma_f32_16x16x32_bf16 v[0:3], v[152:155], v[206:209], v[0:3]
	v_mfma_f32_16x16x32_bf16 v[52:55], v[148:151], v[164:167], v[52:55]
	v_mfma_f32_16x16x32_bf16 v[48:51], v[156:159], v[164:167], v[48:51]
	v_mfma_f32_16x16x32_bf16 v[36:39], v[148:151], v[172:175], v[36:39]
	v_mfma_f32_16x16x32_bf16 v[32:35], v[156:159], v[172:175], v[32:35]
	v_mfma_f32_16x16x32_bf16 v[20:23], v[148:151], v[202:205], v[20:23]
	v_mfma_f32_16x16x32_bf16 v[16:19], v[156:159], v[202:205], v[16:19]
	v_mfma_f32_16x16x32_bf16 v[4:7], v[148:151], v[210:213], v[4:7]
	v_mfma_f32_16x16x32_bf16 v[0:3], v[156:159], v[210:213], v[0:3]
	s_barrier
	s_add_i32 s0, 0, 0x18000
	s_add_i32 s1, 0, 0x1c000
	v_add_u32_e32 v108, s0, v242
	v_add_u32_e32 v156, s1, v242
	ds_read_b128 v[96:99], v108
	ds_read_b128 v[100:103], v108 offset:1024
	ds_read_b128 v[104:107], v108 offset:2048
	ds_read_b128 v[108:111], v108 offset:3072
	ds_read_b128 v[144:147], v156
	ds_read_b128 v[148:151], v156 offset:1024
	ds_read_b128 v[152:155], v156 offset:2048
	ds_read_b128 v[156:159], v156 offset:3072
	s_add_u32 s66, s66, 0x40000
	s_addc_u32 s67, s67, 0
	s_mov_b32 m0, s34
	v_lshl_add_u64 v[240:241], s[66:67], 0, v[192:193]
	ds_read_b128 v[160:163], v244 offset:32768
	ds_read_b128 v[164:167], v244 offset:33792
	ds_read_b128 v[168:171], v244 offset:34816
	ds_read_b128 v[172:175], v244 offset:35840
	ds_read_b128 v[198:201], v244 offset:36864
	ds_read_b128 v[202:205], v244 offset:37888
	ds_read_b128 v[206:209], v244 offset:38912
	ds_read_b128 v[210:213], v244 offset:39936
	global_load_lds_dwordx4 v[240:241], off
	v_lshl_add_u64 v[240:241], s[66:67], 0, v[190:191]
	s_mov_b32 m0, s35
	s_nop 0
	global_load_lds_dwordx4 v[240:241], off
	s_waitcnt vmcnt(8)
	s_waitcnt lgkmcnt(0)
	s_barrier
	s_waitcnt lgkmcnt(0)
	v_mfma_f32_16x16x32_bf16 v[136:139], v[96:99], v[160:163], v[136:139]
	v_mfma_f32_16x16x32_bf16 v[140:143], v[104:107], v[160:163], v[140:143]
	v_mfma_f32_16x16x32_bf16 v[124:127], v[96:99], v[168:171], v[124:127]
	v_mfma_f32_16x16x32_bf16 v[120:123], v[104:107], v[168:171], v[120:123]
	v_mfma_f32_16x16x32_bf16 v[92:95], v[96:99], v[198:201], v[92:95]
	v_mfma_f32_16x16x32_bf16 v[88:91], v[104:107], v[198:201], v[88:91]
	v_mfma_f32_16x16x32_bf16 v[76:79], v[96:99], v[206:209], v[76:79]
	v_mfma_f32_16x16x32_bf16 v[72:75], v[104:107], v[206:209], v[72:75]
	v_mfma_f32_16x16x32_bf16 v[136:139], v[100:103], v[164:167], v[136:139]
	v_mfma_f32_16x16x32_bf16 v[140:143], v[108:111], v[164:167], v[140:143]
	v_mfma_f32_16x16x32_bf16 v[124:127], v[100:103], v[172:175], v[124:127]
	v_mfma_f32_16x16x32_bf16 v[120:123], v[108:111], v[172:175], v[120:123]
	v_mfma_f32_16x16x32_bf16 v[92:95], v[100:103], v[202:205], v[92:95]
	v_mfma_f32_16x16x32_bf16 v[88:91], v[108:111], v[202:205], v[88:91]
	v_mfma_f32_16x16x32_bf16 v[76:79], v[100:103], v[210:213], v[76:79]
	v_mfma_f32_16x16x32_bf16 v[72:75], v[108:111], v[210:213], v[72:75]
	v_mfma_f32_16x16x32_bf16 v[132:135], v[144:147], v[160:163], v[132:135]
	v_mfma_f32_16x16x32_bf16 v[128:131], v[152:155], v[160:163], v[128:131]
	v_mfma_f32_16x16x32_bf16 v[116:119], v[144:147], v[168:171], v[116:119]
	v_mfma_f32_16x16x32_bf16 v[112:115], v[152:155], v[168:171], v[112:115]
	v_mfma_f32_16x16x32_bf16 v[84:87], v[144:147], v[198:201], v[84:87]
	v_mfma_f32_16x16x32_bf16 v[80:83], v[152:155], v[198:201], v[80:83]
	v_mfma_f32_16x16x32_bf16 v[68:71], v[144:147], v[206:209], v[68:71]
	v_mfma_f32_16x16x32_bf16 v[64:67], v[152:155], v[206:209], v[64:67]
	v_mfma_f32_16x16x32_bf16 v[132:135], v[148:151], v[164:167], v[132:135]
	v_mfma_f32_16x16x32_bf16 v[128:131], v[156:159], v[164:167], v[128:131]
	v_mfma_f32_16x16x32_bf16 v[116:119], v[148:151], v[172:175], v[116:119]
	v_mfma_f32_16x16x32_bf16 v[112:115], v[156:159], v[172:175], v[112:115]
	v_mfma_f32_16x16x32_bf16 v[84:87], v[148:151], v[202:205], v[84:87]
	v_mfma_f32_16x16x32_bf16 v[80:83], v[156:159], v[202:205], v[80:83]
	v_mfma_f32_16x16x32_bf16 v[68:71], v[148:151], v[210:213], v[68:71]
	v_mfma_f32_16x16x32_bf16 v[64:67], v[156:159], v[210:213], v[64:67]
	s_barrier
	s_add_i32 s0, s0, s30
	v_lshl_add_u64 v[214:215], v[214:215], 0, s[96:97]
	s_mov_b32 m0, s0
	ds_read_b128 v[160:163], v244 offset:49152
	ds_read_b128 v[164:167], v244 offset:50176
	ds_read_b128 v[168:171], v244 offset:51200
	ds_read_b128 v[172:175], v244 offset:52224
	ds_read_b128 v[198:201], v244 offset:53248
	ds_read_b128 v[202:205], v244 offset:54272
	ds_read_b128 v[206:209], v244 offset:55296
	ds_read_b128 v[210:213], v244 offset:56320
	global_load_lds_dwordx4 v[214:215], off
	v_lshl_add_u64 v[214:215], v[216:217], 0, s[96:97]
	s_add_i32 m0, s0, 0x2000
	s_add_i32 s0, s1, s30
	global_load_lds_dwordx4 v[214:215], off
	v_lshl_add_u64 v[214:215], v[218:219], 0, s[96:97]
	s_mov_b32 m0, s0
	s_nop 0
	global_load_lds_dwordx4 v[214:215], off
	v_lshl_add_u64 v[214:215], v[220:221], 0, s[96:97]
	s_add_i32 m0, s0, 0x2000
	s_nop 0
	global_load_lds_dwordx4 v[214:215], off
	v_lshl_add_u64 v[214:215], v[222:223], 0, s[96:97]
	s_mov_b32 m0, s41
	s_nop 0
	global_load_lds_dwordx4 v[214:215], off
	v_lshl_add_u64 v[214:215], v[238:239], 0, s[96:97]
	s_mov_b32 m0, s42
	s_nop 0
	global_load_lds_dwordx4 v[214:215], off
	s_waitcnt vmcnt(8)
	s_waitcnt lgkmcnt(0)
	s_barrier
	s_waitcnt lgkmcnt(0)
	v_mfma_f32_16x16x32_bf16 v[60:63], v[96:99], v[160:163], v[60:63]
	v_mfma_f32_16x16x32_bf16 v[56:59], v[104:107], v[160:163], v[56:59]
	v_mfma_f32_16x16x32_bf16 v[44:47], v[96:99], v[168:171], v[44:47]
	v_mfma_f32_16x16x32_bf16 v[40:43], v[104:107], v[168:171], v[40:43]
	v_mfma_f32_16x16x32_bf16 v[28:31], v[96:99], v[198:201], v[28:31]
	v_mfma_f32_16x16x32_bf16 v[24:27], v[104:107], v[198:201], v[24:27]
	v_mfma_f32_16x16x32_bf16 v[12:15], v[96:99], v[206:209], v[12:15]
	v_mfma_f32_16x16x32_bf16 v[8:11], v[104:107], v[206:209], v[8:11]
	v_mfma_f32_16x16x32_bf16 v[60:63], v[100:103], v[164:167], v[60:63]
	v_mfma_f32_16x16x32_bf16 v[56:59], v[108:111], v[164:167], v[56:59]
	v_mfma_f32_16x16x32_bf16 v[44:47], v[100:103], v[172:175], v[44:47]
	v_mfma_f32_16x16x32_bf16 v[40:43], v[108:111], v[172:175], v[40:43]
	v_mfma_f32_16x16x32_bf16 v[28:31], v[100:103], v[202:205], v[28:31]
	v_mfma_f32_16x16x32_bf16 v[24:27], v[108:111], v[202:205], v[24:27]
	v_mfma_f32_16x16x32_bf16 v[12:15], v[100:103], v[210:213], v[12:15]
	v_mfma_f32_16x16x32_bf16 v[8:11], v[108:111], v[210:213], v[8:11]
	v_mfma_f32_16x16x32_bf16 v[52:55], v[144:147], v[160:163], v[52:55]
	v_mfma_f32_16x16x32_bf16 v[48:51], v[152:155], v[160:163], v[48:51]
	v_mfma_f32_16x16x32_bf16 v[36:39], v[144:147], v[168:171], v[36:39]
	v_mfma_f32_16x16x32_bf16 v[32:35], v[152:155], v[168:171], v[32:35]
	v_mfma_f32_16x16x32_bf16 v[20:23], v[144:147], v[198:201], v[20:23]
	v_mfma_f32_16x16x32_bf16 v[16:19], v[152:155], v[198:201], v[16:19]
	v_mfma_f32_16x16x32_bf16 v[4:7], v[144:147], v[206:209], v[4:7]
	v_mfma_f32_16x16x32_bf16 v[0:3], v[152:155], v[206:209], v[0:3]
	v_mfma_f32_16x16x32_bf16 v[52:55], v[148:151], v[164:167], v[52:55]
	v_mfma_f32_16x16x32_bf16 v[48:51], v[156:159], v[164:167], v[48:51]
	v_mfma_f32_16x16x32_bf16 v[36:39], v[148:151], v[172:175], v[36:39]
	v_mfma_f32_16x16x32_bf16 v[32:35], v[156:159], v[172:175], v[32:35]
	v_mfma_f32_16x16x32_bf16 v[20:23], v[148:151], v[202:205], v[20:23]
	v_mfma_f32_16x16x32_bf16 v[16:19], v[156:159], v[202:205], v[16:19]
	v_mfma_f32_16x16x32_bf16 v[4:7], v[148:151], v[210:213], v[4:7]
	v_mfma_f32_16x16x32_bf16 v[0:3], v[156:159], v[210:213], v[0:3]
	s_barrier
	s_add_u32 s6, s6, 0x100
	s_addc_u32 s7, s7, 0
	s_add_u32 s65, s65, 0x100
	s_addc_u32 s87, s87, 0
	s_cmp_ge_i32 s88, s36
	s_mov_b32 s66, s88
	s_cbranch_scc0 .LBB0_1397
	v_readlane_b32 s65, v254, 48

.LBB0_1538:
	s_add_i32 s50, s2, 2
	s_add_u32 s0, s6, 0xfffc0080
	s_addc_u32 s1, s7, -1
	s_add_i32 s51, 0, 0x10000
	s_cmp_eq_u32 s41, s2
	s_cselect_b32 s3, s19, s1
	s_cselect_b32 s2, s48, s0
	v_add_u32_e32 v143, s51, v141
	s_cselect_b32 s55, s21, s25
	s_cselect_b32 s54, s20, s24
	s_add_i32 s0, 0, 0x14000
	ds_read_b128 v[144:147], v143
	ds_read_b128 v[148:151], v143 offset:1024
	ds_read_b128 v[152:155], v143 offset:2048
	ds_read_b128 v[156:159], v143 offset:3072
	v_add_u32_e32 v143, s0, v141
	ds_read_b128 v[160:163], v143
	ds_read_b128 v[164:167], v143 offset:1024
	ds_read_b128 v[168:171], v143 offset:2048
	ds_read_b128 v[172:175], v143 offset:3072
	v_lshl_add_u64 v[220:221], s[6:7], 0, v[136:137]
	s_add_i32 m0, s31, 0xc000
	ds_read_b128 v[188:191], v142
	ds_read_b128 v[192:195], v142 offset:1024
	ds_read_b128 v[196:199], v142 offset:2048
	ds_read_b128 v[200:203], v142 offset:3072
	ds_read_b128 v[204:207], v142 offset:4096
	ds_read_b128 v[208:211], v142 offset:5120
	ds_read_b128 v[212:215], v142 offset:6144
	ds_read_b128 v[216:219], v142 offset:7168
	global_load_lds_dwordx4 v[220:221], off
	v_lshl_add_u64 v[220:221], s[6:7], 0, v[138:139]
	s_add_i32 m0, s31, 0xe000
	s_nop 0
	global_load_lds_dwordx4 v[220:221], off
	s_waitcnt vmcnt(8)
	s_waitcnt lgkmcnt(0)
	s_barrier
	s_waitcnt lgkmcnt(0)
	v_mfma_f32_16x16x32_bf16 v[120:123], v[144:147], v[188:191], v[120:123]
	v_mfma_f32_16x16x32_bf16 v[124:127], v[152:155], v[188:191], v[124:127]
	v_mfma_f32_16x16x32_bf16 v[108:111], v[144:147], v[196:199], v[108:111]
	v_mfma_f32_16x16x32_bf16 v[104:107], v[152:155], v[196:199], v[104:107]
	v_mfma_f32_16x16x32_bf16 v[92:95], v[144:147], v[204:207], v[92:95]
	v_mfma_f32_16x16x32_bf16 v[88:91], v[152:155], v[204:207], v[88:91]
	v_mfma_f32_16x16x32_bf16 v[76:79], v[144:147], v[212:215], v[76:79]
	v_mfma_f32_16x16x32_bf16 v[72:75], v[152:155], v[212:215], v[72:75]
	v_mfma_f32_16x16x32_bf16 v[120:123], v[148:151], v[192:195], v[120:123]
	v_mfma_f32_16x16x32_bf16 v[124:127], v[156:159], v[192:195], v[124:127]
	v_mfma_f32_16x16x32_bf16 v[108:111], v[148:151], v[200:203], v[108:111]
	v_mfma_f32_16x16x32_bf16 v[104:107], v[156:159], v[200:203], v[104:107]
	v_mfma_f32_16x16x32_bf16 v[92:95], v[148:151], v[208:211], v[92:95]
	v_mfma_f32_16x16x32_bf16 v[88:91], v[156:159], v[208:211], v[88:91]
	v_mfma_f32_16x16x32_bf16 v[76:79], v[148:151], v[216:219], v[76:79]
	v_mfma_f32_16x16x32_bf16 v[72:75], v[156:159], v[216:219], v[72:75]
	v_mfma_f32_16x16x32_bf16 v[116:119], v[160:163], v[188:191], v[116:119]
	v_mfma_f32_16x16x32_bf16 v[112:115], v[168:171], v[188:191], v[112:115]
	v_mfma_f32_16x16x32_bf16 v[100:103], v[160:163], v[196:199], v[100:103]
	v_mfma_f32_16x16x32_bf16 v[96:99], v[168:171], v[196:199], v[96:99]
	v_mfma_f32_16x16x32_bf16 v[84:87], v[160:163], v[204:207], v[84:87]
	v_mfma_f32_16x16x32_bf16 v[80:83], v[168:171], v[204:207], v[80:83]
	v_mfma_f32_16x16x32_bf16 v[68:71], v[160:163], v[212:215], v[68:71]
	v_mfma_f32_16x16x32_bf16 v[64:67], v[168:171], v[212:215], v[64:67]
	v_mfma_f32_16x16x32_bf16 v[116:119], v[164:167], v[192:195], v[116:119]
	v_mfma_f32_16x16x32_bf16 v[112:115], v[172:175], v[192:195], v[112:115]
	v_mfma_f32_16x16x32_bf16 v[100:103], v[164:167], v[200:203], v[100:103]
	v_mfma_f32_16x16x32_bf16 v[96:99], v[172:175], v[200:203], v[96:99]
	v_mfma_f32_16x16x32_bf16 v[84:87], v[164:167], v[208:211], v[84:87]
	v_mfma_f32_16x16x32_bf16 v[80:83], v[172:175], v[208:211], v[80:83]
	v_mfma_f32_16x16x32_bf16 v[68:71], v[164:167], v[216:219], v[68:71]
	v_mfma_f32_16x16x32_bf16 v[64:67], v[172:175], v[216:219], v[64:67]
	s_barrier
	s_add_i32 s1, s51, s30
	v_lshl_add_u64 v[220:221], s[54:55], 0, v[176:177]
	s_mov_b32 m0, s1
	ds_read_b128 v[188:191], v142 offset:16384
	ds_read_b128 v[192:195], v142 offset:17408
	ds_read_b128 v[196:199], v142 offset:18432
	ds_read_b128 v[200:203], v142 offset:19456
	ds_read_b128 v[204:207], v142 offset:20480
	ds_read_b128 v[208:211], v142 offset:21504
	ds_read_b128 v[212:215], v142 offset:22528
	ds_read_b128 v[216:219], v142 offset:23552
	global_load_lds_dwordx4 v[220:221], off
	s_add_i32 m0, s1, 0x2000
	v_lshl_add_u64 v[222:223], s[54:55], 0, v[128:129]
	s_add_u32 s54, s54, s8
	s_addc_u32 s55, s55, s9
	s_add_i32 s0, s0, s30
	global_load_lds_dwordx4 v[222:223], off
	v_lshl_add_u64 v[238:239], s[54:55], 0, v[176:177]
	s_mov_b32 m0, s0
	v_lshl_add_u64 v[240:241], s[54:55], 0, v[128:129]
	global_load_lds_dwordx4 v[238:239], off
	s_add_i32 m0, s0, 0x2000
	v_lshl_add_u64 v[242:243], s[2:3], 0, v[132:133]
	global_load_lds_dwordx4 v[240:241], off
	s_mov_b32 m0, s31
	v_lshl_add_u64 v[244:245], s[2:3], 0, v[130:131]
	global_load_lds_dwordx4 v[242:243], off
	s_mov_b32 m0, s33
	s_nop 0
	global_load_lds_dwordx4 v[244:245], off
	s_waitcnt vmcnt(8)
	s_waitcnt lgkmcnt(0)
	s_barrier
	s_waitcnt lgkmcnt(0)
	v_mfma_f32_16x16x32_bf16 v[60:63], v[144:147], v[188:191], v[60:63]
	v_mfma_f32_16x16x32_bf16 v[56:59], v[152:155], v[188:191], v[56:59]
	v_mfma_f32_16x16x32_bf16 v[44:47], v[144:147], v[196:199], v[44:47]
	v_mfma_f32_16x16x32_bf16 v[40:43], v[152:155], v[196:199], v[40:43]
	v_mfma_f32_16x16x32_bf16 v[28:31], v[144:147], v[204:207], v[28:31]
	v_mfma_f32_16x16x32_bf16 v[24:27], v[152:155], v[204:207], v[24:27]
	v_mfma_f32_16x16x32_bf16 v[12:15], v[144:147], v[212:215], v[12:15]
	v_mfma_f32_16x16x32_bf16 v[8:11], v[152:155], v[212:215], v[8:11]
	v_mfma_f32_16x16x32_bf16 v[60:63], v[148:151], v[192:195], v[60:63]
	v_mfma_f32_16x16x32_bf16 v[56:59], v[156:159], v[192:195], v[56:59]
	v_mfma_f32_16x16x32_bf16 v[44:47], v[148:151], v[200:203], v[44:47]
	v_mfma_f32_16x16x32_bf16 v[40:43], v[156:159], v[200:203], v[40:43]
	v_mfma_f32_16x16x32_bf16 v[28:31], v[148:151], v[208:211], v[28:31]
	v_mfma_f32_16x16x32_bf16 v[24:27], v[156:159], v[208:211], v[24:27]
	v_mfma_f32_16x16x32_bf16 v[12:15], v[148:151], v[216:219], v[12:15]
	v_mfma_f32_16x16x32_bf16 v[8:11], v[156:159], v[216:219], v[8:11]
	v_mfma_f32_16x16x32_bf16 v[52:55], v[160:163], v[188:191], v[52:55]
	v_mfma_f32_16x16x32_bf16 v[48:51], v[168:171], v[188:191], v[48:51]
	v_mfma_f32_16x16x32_bf16 v[36:39], v[160:163], v[196:199], v[36:39]
	v_mfma_f32_16x16x32_bf16 v[32:35], v[168:171], v[196:199], v[32:35]
	v_mfma_f32_16x16x32_bf16 v[20:23], v[160:163], v[204:207], v[20:23]
	v_mfma_f32_16x16x32_bf16 v[16:19], v[168:171], v[204:207], v[16:19]
	v_mfma_f32_16x16x32_bf16 v[4:7], v[160:163], v[212:215], v[4:7]
	v_mfma_f32_16x16x32_bf16 v[0:3], v[168:171], v[212:215], v[0:3]
	v_mfma_f32_16x16x32_bf16 v[52:55], v[164:167], v[192:195], v[52:55]
	v_mfma_f32_16x16x32_bf16 v[48:51], v[172:175], v[192:195], v[48:51]
	v_mfma_f32_16x16x32_bf16 v[36:39], v[164:167], v[200:203], v[36:39]
	v_mfma_f32_16x16x32_bf16 v[32:35], v[172:175], v[200:203], v[32:35]
	v_mfma_f32_16x16x32_bf16 v[20:23], v[164:167], v[208:211], v[20:23]
	v_mfma_f32_16x16x32_bf16 v[16:19], v[172:175], v[208:211], v[16:19]
	v_mfma_f32_16x16x32_bf16 v[4:7], v[164:167], v[216:219], v[4:7]
	v_mfma_f32_16x16x32_bf16 v[0:3], v[172:175], v[216:219], v[0:3]
	s_barrier
	s_add_i32 s0, 0, 0x18000
	v_add_u32_e32 v143, s0, v141
	s_add_i32 s1, 0, 0x1c000
	ds_read_b128 v[144:147], v143
	ds_read_b128 v[148:151], v143 offset:1024
	ds_read_b128 v[152:155], v143 offset:2048
	ds_read_b128 v[156:159], v143 offset:3072
	v_add_u32_e32 v143, s1, v141
	ds_read_b128 v[160:163], v143
	ds_read_b128 v[164:167], v143 offset:1024
	ds_read_b128 v[168:171], v143 offset:2048
	ds_read_b128 v[172:175], v143 offset:3072
	s_add_u32 s2, s2, 0x40000
	s_addc_u32 s3, s3, 0
	s_mov_b32 m0, s34
	v_lshl_add_u64 v[246:247], s[2:3], 0, v[132:133]
	ds_read_b128 v[188:191], v142 offset:32768
	ds_read_b128 v[192:195], v142 offset:33792
	ds_read_b128 v[196:199], v142 offset:34816
	ds_read_b128 v[200:203], v142 offset:35840
	ds_read_b128 v[204:207], v142 offset:36864
	ds_read_b128 v[208:211], v142 offset:37888
	ds_read_b128 v[212:215], v142 offset:38912
	ds_read_b128 v[216:219], v142 offset:39936
	global_load_lds_dwordx4 v[246:247], off
	v_lshl_add_u64 v[246:247], s[2:3], 0, v[130:131]
	s_mov_b32 m0, s35
	s_nop 0
	global_load_lds_dwordx4 v[246:247], off
	s_waitcnt vmcnt(8)
	s_waitcnt lgkmcnt(0)
	s_barrier
	s_waitcnt lgkmcnt(0)
	v_mfma_f32_16x16x32_bf16 v[120:123], v[144:147], v[188:191], v[120:123]
	v_mfma_f32_16x16x32_bf16 v[124:127], v[152:155], v[188:191], v[124:127]
	v_mfma_f32_16x16x32_bf16 v[108:111], v[144:147], v[196:199], v[108:111]
	v_mfma_f32_16x16x32_bf16 v[104:107], v[152:155], v[196:199], v[104:107]
	v_mfma_f32_16x16x32_bf16 v[92:95], v[144:147], v[204:207], v[92:95]
	v_mfma_f32_16x16x32_bf16 v[88:91], v[152:155], v[204:207], v[88:91]
	v_mfma_f32_16x16x32_bf16 v[76:79], v[144:147], v[212:215], v[76:79]
	v_mfma_f32_16x16x32_bf16 v[72:75], v[152:155], v[212:215], v[72:75]
	v_mfma_f32_16x16x32_bf16 v[120:123], v[148:151], v[192:195], v[120:123]
	v_mfma_f32_16x16x32_bf16 v[124:127], v[156:159], v[192:195], v[124:127]
	v_mfma_f32_16x16x32_bf16 v[108:111], v[148:151], v[200:203], v[108:111]
	v_mfma_f32_16x16x32_bf16 v[104:107], v[156:159], v[200:203], v[104:107]
	v_mfma_f32_16x16x32_bf16 v[92:95], v[148:151], v[208:211], v[92:95]
	v_mfma_f32_16x16x32_bf16 v[88:91], v[156:159], v[208:211], v[88:91]
	v_mfma_f32_16x16x32_bf16 v[76:79], v[148:151], v[216:219], v[76:79]
	v_mfma_f32_16x16x32_bf16 v[72:75], v[156:159], v[216:219], v[72:75]
	v_mfma_f32_16x16x32_bf16 v[116:119], v[160:163], v[188:191], v[116:119]
	v_mfma_f32_16x16x32_bf16 v[112:115], v[168:171], v[188:191], v[112:115]
	v_mfma_f32_16x16x32_bf16 v[100:103], v[160:163], v[196:199], v[100:103]
	v_mfma_f32_16x16x32_bf16 v[96:99], v[168:171], v[196:199], v[96:99]
	v_mfma_f32_16x16x32_bf16 v[84:87], v[160:163], v[204:207], v[84:87]
	v_mfma_f32_16x16x32_bf16 v[80:83], v[168:171], v[204:207], v[80:83]
	v_mfma_f32_16x16x32_bf16 v[68:71], v[160:163], v[212:215], v[68:71]
	v_mfma_f32_16x16x32_bf16 v[64:67], v[168:171], v[212:215], v[64:67]
	v_mfma_f32_16x16x32_bf16 v[116:119], v[164:167], v[192:195], v[116:119]
	v_mfma_f32_16x16x32_bf16 v[112:115], v[172:175], v[192:195], v[112:115]
	v_mfma_f32_16x16x32_bf16 v[100:103], v[164:167], v[200:203], v[100:103]
	v_mfma_f32_16x16x32_bf16 v[96:99], v[172:175], v[200:203], v[96:99]
	v_mfma_f32_16x16x32_bf16 v[84:87], v[164:167], v[208:211], v[84:87]
	v_mfma_f32_16x16x32_bf16 v[80:83], v[172:175], v[208:211], v[80:83]
	v_mfma_f32_16x16x32_bf16 v[68:71], v[164:167], v[216:219], v[68:71]
	v_mfma_f32_16x16x32_bf16 v[64:67], v[172:175], v[216:219], v[64:67]
	s_barrier
	s_add_i32 s0, s0, s30
	v_lshl_add_u64 v[220:221], v[220:221], 0, s[96:97]
	s_mov_b32 m0, s0
	ds_read_b128 v[188:191], v142 offset:49152
	ds_read_b128 v[192:195], v142 offset:50176
	ds_read_b128 v[196:199], v142 offset:51200
	ds_read_b128 v[200:203], v142 offset:52224
	ds_read_b128 v[204:207], v142 offset:53248
	ds_read_b128 v[208:211], v142 offset:54272
	ds_read_b128 v[212:215], v142 offset:55296
	ds_read_b128 v[216:219], v142 offset:56320
	global_load_lds_dwordx4 v[220:221], off
	v_lshl_add_u64 v[220:221], v[222:223], 0, s[96:97]
	s_add_i32 m0, s0, 0x2000
	s_add_i32 s0, s1, s30
	global_load_lds_dwordx4 v[220:221], off
	v_lshl_add_u64 v[220:221], v[238:239], 0, s[96:97]
	s_mov_b32 m0, s0
	s_nop 0
	global_load_lds_dwordx4 v[220:221], off
	v_lshl_add_u64 v[220:221], v[240:241], 0, s[96:97]
	s_add_i32 m0, s0, 0x2000
	s_nop 0
	global_load_lds_dwordx4 v[220:221], off
	v_lshl_add_u64 v[220:221], v[242:243], 0, s[96:97]
	s_mov_b32 m0, s36
	s_nop 0
	global_load_lds_dwordx4 v[220:221], off
	v_lshl_add_u64 v[220:221], v[244:245], 0, s[96:97]
	s_mov_b32 m0, s37
	s_nop 0
	global_load_lds_dwordx4 v[220:221], off
	s_waitcnt vmcnt(8)
	s_waitcnt lgkmcnt(0)
	s_barrier
	s_waitcnt lgkmcnt(0)
	v_mfma_f32_16x16x32_bf16 v[60:63], v[144:147], v[188:191], v[60:63]
	v_mfma_f32_16x16x32_bf16 v[56:59], v[152:155], v[188:191], v[56:59]
	v_mfma_f32_16x16x32_bf16 v[44:47], v[144:147], v[196:199], v[44:47]
	v_mfma_f32_16x16x32_bf16 v[40:43], v[152:155], v[196:199], v[40:43]
	v_mfma_f32_16x16x32_bf16 v[28:31], v[144:147], v[204:207], v[28:31]
	v_mfma_f32_16x16x32_bf16 v[24:27], v[152:155], v[204:207], v[24:27]
	v_mfma_f32_16x16x32_bf16 v[12:15], v[144:147], v[212:215], v[12:15]
	v_mfma_f32_16x16x32_bf16 v[8:11], v[152:155], v[212:215], v[8:11]
	v_mfma_f32_16x16x32_bf16 v[60:63], v[148:151], v[192:195], v[60:63]
	v_mfma_f32_16x16x32_bf16 v[56:59], v[156:159], v[192:195], v[56:59]
	v_mfma_f32_16x16x32_bf16 v[44:47], v[148:151], v[200:203], v[44:47]
	v_mfma_f32_16x16x32_bf16 v[40:43], v[156:159], v[200:203], v[40:43]
	v_mfma_f32_16x16x32_bf16 v[28:31], v[148:151], v[208:211], v[28:31]
	v_mfma_f32_16x16x32_bf16 v[24:27], v[156:159], v[208:211], v[24:27]
	v_mfma_f32_16x16x32_bf16 v[12:15], v[148:151], v[216:219], v[12:15]
	v_mfma_f32_16x16x32_bf16 v[8:11], v[156:159], v[216:219], v[8:11]
	v_mfma_f32_16x16x32_bf16 v[52:55], v[160:163], v[188:191], v[52:55]
	v_mfma_f32_16x16x32_bf16 v[48:51], v[168:171], v[188:191], v[48:51]
	v_mfma_f32_16x16x32_bf16 v[36:39], v[160:163], v[196:199], v[36:39]
	v_mfma_f32_16x16x32_bf16 v[32:35], v[168:171], v[196:199], v[32:35]
	v_mfma_f32_16x16x32_bf16 v[20:23], v[160:163], v[204:207], v[20:23]
	v_mfma_f32_16x16x32_bf16 v[16:19], v[168:171], v[204:207], v[16:19]
	v_mfma_f32_16x16x32_bf16 v[4:7], v[160:163], v[212:215], v[4:7]
	v_mfma_f32_16x16x32_bf16 v[0:3], v[168:171], v[212:215], v[0:3]
	v_mfma_f32_16x16x32_bf16 v[52:55], v[164:167], v[192:195], v[52:55]
	v_mfma_f32_16x16x32_bf16 v[48:51], v[172:175], v[192:195], v[48:51]
	v_mfma_f32_16x16x32_bf16 v[36:39], v[164:167], v[200:203], v[36:39]
	v_mfma_f32_16x16x32_bf16 v[32:35], v[172:175], v[200:203], v[32:35]
	v_mfma_f32_16x16x32_bf16 v[20:23], v[164:167], v[208:211], v[20:23]
	v_mfma_f32_16x16x32_bf16 v[16:19], v[172:175], v[208:211], v[16:19]
	v_mfma_f32_16x16x32_bf16 v[4:7], v[164:167], v[216:219], v[4:7]
	v_mfma_f32_16x16x32_bf16 v[0:3], v[172:175], v[216:219], v[0:3]
	s_barrier
	s_add_u32 s6, s6, 0x100
	s_addc_u32 s7, s7, 0
	s_add_u32 s24, s24, 0x100
	s_addc_u32 s25, s25, 0
	s_cmp_ge_i32 s50, s40
	s_mov_b32 s2, s50
	s_cbranch_scc0 .LBB0_1538

.LBB0_1616:
	s_add_i32 s48, s20, 2
	s_add_u32 s0, s18, 0x100
	s_addc_u32 s1, s19, 0
	s_add_i32 s54, 0, 0x10000
	s_cmp_eq_u32 s37, s20
	s_cselect_b32 s21, s5, s1
	s_cselect_b32 s20, s4, s0
	s_cselect_b32 s51, s17, s47
	s_cselect_b32 s50, s16, s46
	s_add_i32 s55, 0, 0x14000
	v_add_u32_e32 v76, s54, v161
	v_add_u32_e32 v158, s55, v161
	ds_read_b128 v[64:67], v76
	ds_read_b128 v[68:71], v76 offset:1024
	ds_read_b128 v[72:75], v76 offset:2048
	ds_read_b128 v[76:79], v76 offset:3072
	ds_read_b128 v[154:157], v158
	ds_read_b128 v[164:167], v158 offset:1024
	ds_read_b128 v[168:171], v158 offset:2048
	ds_read_b128 v[172:175], v158 offset:3072
	v_lshl_add_u64 v[158:159], s[18:19], 0, v[150:151]
	s_add_i32 m0, s27, 0xc000
	ds_read_b128 v[188:191], v163
	ds_read_b128 v[192:195], v163 offset:1024
	ds_read_b128 v[196:199], v163 offset:2048
	ds_read_b128 v[200:203], v163 offset:3072
	ds_read_b128 v[204:207], v163 offset:4096
	ds_read_b128 v[208:211], v163 offset:5120
	ds_read_b128 v[212:215], v163 offset:6144
	ds_read_b128 v[216:219], v163 offset:7168
	global_load_lds_dwordx4 v[158:159], off
	v_lshl_add_u64 v[158:159], s[18:19], 0, v[152:153]
	s_add_i32 m0, s27, 0xe000
	s_nop 0
	global_load_lds_dwordx4 v[158:159], off
	s_waitcnt vmcnt(8)
	s_waitcnt lgkmcnt(0)
	s_barrier
	s_waitcnt lgkmcnt(0)
	v_mfma_f32_16x16x32_bf16 v[140:143], v[64:67], v[188:191], v[140:143]
	v_mfma_f32_16x16x32_bf16 v[136:139], v[72:75], v[188:191], v[136:139]
	v_mfma_f32_16x16x32_bf16 v[124:127], v[64:67], v[196:199], v[124:127]
	v_mfma_f32_16x16x32_bf16 v[120:123], v[72:75], v[196:199], v[120:123]
	v_mfma_f32_16x16x32_bf16 v[108:111], v[64:67], v[204:207], v[108:111]
	v_mfma_f32_16x16x32_bf16 v[104:107], v[72:75], v[204:207], v[104:107]
	v_mfma_f32_16x16x32_bf16 v[92:95], v[64:67], v[212:215], v[92:95]
	v_mfma_f32_16x16x32_bf16 v[88:91], v[72:75], v[212:215], v[88:91]
	v_mfma_f32_16x16x32_bf16 v[140:143], v[68:71], v[192:195], v[140:143]
	v_mfma_f32_16x16x32_bf16 v[136:139], v[76:79], v[192:195], v[136:139]
	v_mfma_f32_16x16x32_bf16 v[124:127], v[68:71], v[200:203], v[124:127]
	v_mfma_f32_16x16x32_bf16 v[120:123], v[76:79], v[200:203], v[120:123]
	v_mfma_f32_16x16x32_bf16 v[108:111], v[68:71], v[208:211], v[108:111]
	v_mfma_f32_16x16x32_bf16 v[104:107], v[76:79], v[208:211], v[104:107]
	v_mfma_f32_16x16x32_bf16 v[92:95], v[68:71], v[216:219], v[92:95]
	v_mfma_f32_16x16x32_bf16 v[88:91], v[76:79], v[216:219], v[88:91]
	v_mfma_f32_16x16x32_bf16 v[132:135], v[154:157], v[188:191], v[132:135]
	v_mfma_f32_16x16x32_bf16 v[128:131], v[168:171], v[188:191], v[128:131]
	v_mfma_f32_16x16x32_bf16 v[116:119], v[154:157], v[196:199], v[116:119]
	v_mfma_f32_16x16x32_bf16 v[112:115], v[168:171], v[196:199], v[112:115]
	v_mfma_f32_16x16x32_bf16 v[100:103], v[154:157], v[204:207], v[100:103]
	v_mfma_f32_16x16x32_bf16 v[96:99], v[168:171], v[204:207], v[96:99]
	v_mfma_f32_16x16x32_bf16 v[84:87], v[154:157], v[212:215], v[84:87]
	v_mfma_f32_16x16x32_bf16 v[80:83], v[168:171], v[212:215], v[80:83]
	v_mfma_f32_16x16x32_bf16 v[132:135], v[164:167], v[192:195], v[132:135]
	v_mfma_f32_16x16x32_bf16 v[128:131], v[172:175], v[192:195], v[128:131]
	v_mfma_f32_16x16x32_bf16 v[116:119], v[164:167], v[200:203], v[116:119]
	v_mfma_f32_16x16x32_bf16 v[112:115], v[172:175], v[200:203], v[112:115]
	v_mfma_f32_16x16x32_bf16 v[100:103], v[164:167], v[208:211], v[100:103]
	v_mfma_f32_16x16x32_bf16 v[96:99], v[172:175], v[208:211], v[96:99]
	v_mfma_f32_16x16x32_bf16 v[84:87], v[164:167], v[216:219], v[84:87]
	v_mfma_f32_16x16x32_bf16 v[80:83], v[172:175], v[216:219], v[80:83]
	s_barrier
	s_add_i32 s18, s54, s26
	v_lshl_add_u64 v[158:159], s[50:51], 0, v[176:177]
	s_mov_b32 m0, s18
	ds_read_b128 v[188:191], v163 offset:16384
	ds_read_b128 v[192:195], v163 offset:17408
	ds_read_b128 v[196:199], v163 offset:18432
	ds_read_b128 v[200:203], v163 offset:19456
	ds_read_b128 v[204:207], v163 offset:20480
	ds_read_b128 v[208:211], v163 offset:21504
	ds_read_b128 v[212:215], v163 offset:22528
	ds_read_b128 v[216:219], v163 offset:23552
	global_load_lds_dwordx4 v[158:159], off
	s_add_i32 m0, s18, 0x2000
	s_add_u32 s18, s50, s6
	v_lshl_add_u64 v[220:221], s[50:51], 0, v[144:145]
	s_addc_u32 s19, s51, s7
	s_add_i32 s50, s55, s26
	global_load_lds_dwordx4 v[220:221], off
	v_lshl_add_u64 v[222:223], s[18:19], 0, v[176:177]
	s_mov_b32 m0, s50
	v_lshl_add_u64 v[238:239], s[18:19], 0, v[144:145]
	global_load_lds_dwordx4 v[222:223], off
	s_add_i32 m0, s50, 0x2000
	v_lshl_add_u64 v[240:241], s[20:21], 0, v[148:149]
	global_load_lds_dwordx4 v[238:239], off
	s_mov_b32 m0, s27
	v_lshl_add_u64 v[242:243], s[20:21], 0, v[146:147]
	global_load_lds_dwordx4 v[240:241], off
	s_mov_b32 m0, s28
	s_nop 0
	global_load_lds_dwordx4 v[242:243], off
	s_waitcnt vmcnt(8)
	s_waitcnt lgkmcnt(0)
	s_barrier
	s_waitcnt lgkmcnt(0)
	v_mfma_f32_16x16x32_bf16 v[60:63], v[64:67], v[188:191], v[60:63]
	v_mfma_f32_16x16x32_bf16 v[56:59], v[72:75], v[188:191], v[56:59]
	v_mfma_f32_16x16x32_bf16 v[44:47], v[64:67], v[196:199], v[44:47]
	v_mfma_f32_16x16x32_bf16 v[40:43], v[72:75], v[196:199], v[40:43]
	v_mfma_f32_16x16x32_bf16 v[28:31], v[64:67], v[204:207], v[28:31]
	v_mfma_f32_16x16x32_bf16 v[24:27], v[72:75], v[204:207], v[24:27]
	v_mfma_f32_16x16x32_bf16 v[12:15], v[64:67], v[212:215], v[12:15]
	v_mfma_f32_16x16x32_bf16 v[8:11], v[72:75], v[212:215], v[8:11]
	v_mfma_f32_16x16x32_bf16 v[60:63], v[68:71], v[192:195], v[60:63]
	v_mfma_f32_16x16x32_bf16 v[56:59], v[76:79], v[192:195], v[56:59]
	v_mfma_f32_16x16x32_bf16 v[44:47], v[68:71], v[200:203], v[44:47]
	v_mfma_f32_16x16x32_bf16 v[40:43], v[76:79], v[200:203], v[40:43]
	v_mfma_f32_16x16x32_bf16 v[28:31], v[68:71], v[208:211], v[28:31]
	v_mfma_f32_16x16x32_bf16 v[24:27], v[76:79], v[208:211], v[24:27]
	v_mfma_f32_16x16x32_bf16 v[12:15], v[68:71], v[216:219], v[12:15]
	v_mfma_f32_16x16x32_bf16 v[8:11], v[76:79], v[216:219], v[8:11]
	v_mfma_f32_16x16x32_bf16 v[52:55], v[154:157], v[188:191], v[52:55]
	v_mfma_f32_16x16x32_bf16 v[48:51], v[168:171], v[188:191], v[48:51]
	v_mfma_f32_16x16x32_bf16 v[36:39], v[154:157], v[196:199], v[36:39]
	v_mfma_f32_16x16x32_bf16 v[32:35], v[168:171], v[196:199], v[32:35]
	v_mfma_f32_16x16x32_bf16 v[20:23], v[154:157], v[204:207], v[20:23]
	v_mfma_f32_16x16x32_bf16 v[16:19], v[168:171], v[204:207], v[16:19]
	v_mfma_f32_16x16x32_bf16 v[4:7], v[154:157], v[212:215], v[4:7]
	v_mfma_f32_16x16x32_bf16 v[0:3], v[168:171], v[212:215], v[0:3]
	v_mfma_f32_16x16x32_bf16 v[52:55], v[164:167], v[192:195], v[52:55]
	v_mfma_f32_16x16x32_bf16 v[48:51], v[172:175], v[192:195], v[48:51]
	v_mfma_f32_16x16x32_bf16 v[36:39], v[164:167], v[200:203], v[36:39]
	v_mfma_f32_16x16x32_bf16 v[32:35], v[172:175], v[200:203], v[32:35]
	v_mfma_f32_16x16x32_bf16 v[20:23], v[164:167], v[208:211], v[20:23]
	v_mfma_f32_16x16x32_bf16 v[16:19], v[172:175], v[208:211], v[16:19]
	v_mfma_f32_16x16x32_bf16 v[4:7], v[164:167], v[216:219], v[4:7]
	v_mfma_f32_16x16x32_bf16 v[0:3], v[172:175], v[216:219], v[0:3]
	s_barrier
	s_add_i32 s50, 0, 0x18000
	s_add_i32 s51, 0, 0x1c000
	v_add_u32_e32 v76, s50, v161
	v_add_u32_e32 v172, s51, v161
	ds_read_b128 v[64:67], v76
	ds_read_b128 v[68:71], v76 offset:1024
	ds_read_b128 v[72:75], v76 offset:2048
	ds_read_b128 v[76:79], v76 offset:3072
	ds_read_b128 v[154:157], v172
	ds_read_b128 v[164:167], v172 offset:1024
	ds_read_b128 v[168:171], v172 offset:2048
	ds_read_b128 v[172:175], v172 offset:3072
	s_add_u32 s18, s20, 0xb0000
	s_addc_u32 s19, s21, 0
	s_mov_b32 m0, s29
	v_lshl_add_u64 v[244:245], s[18:19], 0, v[148:149]
	ds_read_b128 v[188:191], v163 offset:32768
	ds_read_b128 v[192:195], v163 offset:33792
	ds_read_b128 v[196:199], v163 offset:34816
	ds_read_b128 v[200:203], v163 offset:35840
	ds_read_b128 v[204:207], v163 offset:36864
	ds_read_b128 v[208:211], v163 offset:37888
	ds_read_b128 v[212:215], v163 offset:38912
	ds_read_b128 v[216:219], v163 offset:39936
	global_load_lds_dwordx4 v[244:245], off
	v_lshl_add_u64 v[244:245], s[18:19], 0, v[146:147]
	s_mov_b32 m0, s30
	s_nop 0
	global_load_lds_dwordx4 v[244:245], off
	s_waitcnt vmcnt(8)
	s_waitcnt lgkmcnt(0)
	s_barrier
	s_waitcnt lgkmcnt(0)
	v_mfma_f32_16x16x32_bf16 v[140:143], v[64:67], v[188:191], v[140:143]
	v_mfma_f32_16x16x32_bf16 v[136:139], v[72:75], v[188:191], v[136:139]
	v_mfma_f32_16x16x32_bf16 v[124:127], v[64:67], v[196:199], v[124:127]
	v_mfma_f32_16x16x32_bf16 v[120:123], v[72:75], v[196:199], v[120:123]
	v_mfma_f32_16x16x32_bf16 v[108:111], v[64:67], v[204:207], v[108:111]
	v_mfma_f32_16x16x32_bf16 v[104:107], v[72:75], v[204:207], v[104:107]
	v_mfma_f32_16x16x32_bf16 v[92:95], v[64:67], v[212:215], v[92:95]
	v_mfma_f32_16x16x32_bf16 v[88:91], v[72:75], v[212:215], v[88:91]
	v_mfma_f32_16x16x32_bf16 v[140:143], v[68:71], v[192:195], v[140:143]
	v_mfma_f32_16x16x32_bf16 v[136:139], v[76:79], v[192:195], v[136:139]
	v_mfma_f32_16x16x32_bf16 v[124:127], v[68:71], v[200:203], v[124:127]
	v_mfma_f32_16x16x32_bf16 v[120:123], v[76:79], v[200:203], v[120:123]
	v_mfma_f32_16x16x32_bf16 v[108:111], v[68:71], v[208:211], v[108:111]
	v_mfma_f32_16x16x32_bf16 v[104:107], v[76:79], v[208:211], v[104:107]
	v_mfma_f32_16x16x32_bf16 v[92:95], v[68:71], v[216:219], v[92:95]
	v_mfma_f32_16x16x32_bf16 v[88:91], v[76:79], v[216:219], v[88:91]
	v_mfma_f32_16x16x32_bf16 v[132:135], v[154:157], v[188:191], v[132:135]
	v_mfma_f32_16x16x32_bf16 v[128:131], v[168:171], v[188:191], v[128:131]
	v_mfma_f32_16x16x32_bf16 v[116:119], v[154:157], v[196:199], v[116:119]
	v_mfma_f32_16x16x32_bf16 v[112:115], v[168:171], v[196:199], v[112:115]
	v_mfma_f32_16x16x32_bf16 v[100:103], v[154:157], v[204:207], v[100:103]
	v_mfma_f32_16x16x32_bf16 v[96:99], v[168:171], v[204:207], v[96:99]
	v_mfma_f32_16x16x32_bf16 v[84:87], v[154:157], v[212:215], v[84:87]
	v_mfma_f32_16x16x32_bf16 v[80:83], v[168:171], v[212:215], v[80:83]
	v_mfma_f32_16x16x32_bf16 v[132:135], v[164:167], v[192:195], v[132:135]
	v_mfma_f32_16x16x32_bf16 v[128:131], v[172:175], v[192:195], v[128:131]
	v_mfma_f32_16x16x32_bf16 v[116:119], v[164:167], v[200:203], v[116:119]
	v_mfma_f32_16x16x32_bf16 v[112:115], v[172:175], v[200:203], v[112:115]
	v_mfma_f32_16x16x32_bf16 v[100:103], v[164:167], v[208:211], v[100:103]
	v_mfma_f32_16x16x32_bf16 v[96:99], v[172:175], v[208:211], v[96:99]
	v_mfma_f32_16x16x32_bf16 v[84:87], v[164:167], v[216:219], v[84:87]
	v_mfma_f32_16x16x32_bf16 v[80:83], v[172:175], v[216:219], v[80:83]
	s_barrier
	s_add_i32 s18, s50, s26
	v_lshl_add_u64 v[158:159], v[158:159], 0, s[96:97]
	s_mov_b32 m0, s18
	ds_read_b128 v[188:191], v163 offset:49152
	ds_read_b128 v[192:195], v163 offset:50176
	ds_read_b128 v[196:199], v163 offset:51200
	ds_read_b128 v[200:203], v163 offset:52224
	ds_read_b128 v[204:207], v163 offset:53248
	ds_read_b128 v[208:211], v163 offset:54272
	ds_read_b128 v[212:215], v163 offset:55296
	ds_read_b128 v[216:219], v163 offset:56320
	global_load_lds_dwordx4 v[158:159], off
	v_lshl_add_u64 v[158:159], v[220:221], 0, s[96:97]
	s_add_i32 m0, s18, 0x2000
	s_add_i32 s18, s51, s26
	global_load_lds_dwordx4 v[158:159], off
	v_lshl_add_u64 v[158:159], v[222:223], 0, s[96:97]
	s_mov_b32 m0, s18
	s_nop 0
	global_load_lds_dwordx4 v[158:159], off
	v_lshl_add_u64 v[158:159], v[238:239], 0, s[96:97]
	s_add_i32 m0, s18, 0x2000
	s_nop 0
	global_load_lds_dwordx4 v[158:159], off
	v_lshl_add_u64 v[158:159], v[240:241], 0, s[96:97]
	s_mov_b32 m0, s34
	s_nop 0
	global_load_lds_dwordx4 v[158:159], off
	v_lshl_add_u64 v[158:159], v[242:243], 0, s[96:97]
	s_mov_b32 m0, s35
	s_nop 0
	global_load_lds_dwordx4 v[158:159], off
	s_waitcnt vmcnt(8)
	s_waitcnt lgkmcnt(0)
	s_barrier
	s_waitcnt lgkmcnt(0)
	v_mfma_f32_16x16x32_bf16 v[60:63], v[64:67], v[188:191], v[60:63]
	v_mfma_f32_16x16x32_bf16 v[56:59], v[72:75], v[188:191], v[56:59]
	v_mfma_f32_16x16x32_bf16 v[44:47], v[64:67], v[196:199], v[44:47]
	v_mfma_f32_16x16x32_bf16 v[40:43], v[72:75], v[196:199], v[40:43]
	v_mfma_f32_16x16x32_bf16 v[28:31], v[64:67], v[204:207], v[28:31]
	v_mfma_f32_16x16x32_bf16 v[24:27], v[72:75], v[204:207], v[24:27]
	v_mfma_f32_16x16x32_bf16 v[12:15], v[64:67], v[212:215], v[12:15]
	v_mfma_f32_16x16x32_bf16 v[8:11], v[72:75], v[212:215], v[8:11]
	v_mfma_f32_16x16x32_bf16 v[60:63], v[68:71], v[192:195], v[60:63]
	v_mfma_f32_16x16x32_bf16 v[56:59], v[76:79], v[192:195], v[56:59]
	v_mfma_f32_16x16x32_bf16 v[44:47], v[68:71], v[200:203], v[44:47]
	v_mfma_f32_16x16x32_bf16 v[40:43], v[76:79], v[200:203], v[40:43]
	v_mfma_f32_16x16x32_bf16 v[28:31], v[68:71], v[208:211], v[28:31]
	v_mfma_f32_16x16x32_bf16 v[24:27], v[76:79], v[208:211], v[24:27]
	v_mfma_f32_16x16x32_bf16 v[12:15], v[68:71], v[216:219], v[12:15]
	v_mfma_f32_16x16x32_bf16 v[8:11], v[76:79], v[216:219], v[8:11]
	v_mfma_f32_16x16x32_bf16 v[52:55], v[154:157], v[188:191], v[52:55]
	v_mfma_f32_16x16x32_bf16 v[48:51], v[168:171], v[188:191], v[48:51]
	v_mfma_f32_16x16x32_bf16 v[36:39], v[154:157], v[196:199], v[36:39]
	v_mfma_f32_16x16x32_bf16 v[32:35], v[168:171], v[196:199], v[32:35]
	v_mfma_f32_16x16x32_bf16 v[20:23], v[154:157], v[204:207], v[20:23]
	v_mfma_f32_16x16x32_bf16 v[16:19], v[168:171], v[204:207], v[16:19]
	v_mfma_f32_16x16x32_bf16 v[4:7], v[154:157], v[212:215], v[4:7]
	v_mfma_f32_16x16x32_bf16 v[0:3], v[168:171], v[212:215], v[0:3]
	v_mfma_f32_16x16x32_bf16 v[52:55], v[164:167], v[192:195], v[52:55]
	v_mfma_f32_16x16x32_bf16 v[48:51], v[172:175], v[192:195], v[48:51]
	v_mfma_f32_16x16x32_bf16 v[36:39], v[164:167], v[200:203], v[36:39]
	v_mfma_f32_16x16x32_bf16 v[32:35], v[172:175], v[200:203], v[32:35]
	v_mfma_f32_16x16x32_bf16 v[20:23], v[164:167], v[208:211], v[20:23]
	v_mfma_f32_16x16x32_bf16 v[16:19], v[172:175], v[208:211], v[16:19]
	v_mfma_f32_16x16x32_bf16 v[4:7], v[164:167], v[216:219], v[4:7]
	v_mfma_f32_16x16x32_bf16 v[0:3], v[172:175], v[216:219], v[0:3]
	s_barrier
	s_add_u32 s46, s46, 0x100
	s_addc_u32 s47, s47, 0
	s_cmp_ge_i32 s48, s36
	s_mov_b64 s[18:19], s[0:1]
	s_mov_b32 s20, s48
	s_cbranch_scc0 .LBB0_1616
